# hand-written fused residual+RMSNorm epilogue (down, out-proj): pipelined x loads, y kept in acc regs, no re-read
# speedup vs baseline: 1.0378x; 1.0378x over previous
.LBB0_362:
	v_mov_b32_e32 v12, v216
	s_cmpk_lg_i32 s74, 0x100
	s_waitcnt vmcnt(0)
	s_barrier
	s_cselect_b64 s[0:1], -1, 0
	v_readfirstlane_b32 s23, v12
	s_ashr_i32 s33, s23, 8
	s_bfe_u32 s38, s23, 0x20006
	s_cmp_eq_u32 s93, 44
	s_cselect_b64 s[4:5], -1, 0
	s_cmp_lg_u32 s93, 44
	s_cselect_b64 s[8:9], -1, 0
	s_or_b64 s[0:1], s[0:1], s[8:9]
	s_cmp_gt_i32 s22, 63
	s_cselect_b64 s[8:9], -1, 0
	v_readlane_b32 s78, v254, 8
	s_or_b64 s[0:1], s[0:1], s[8:9]
	v_readlane_b32 s76, v254, 6
	v_readlane_b32 s79, v254, 9
	v_readlane_b32 s80, v254, 21
	v_readlane_b32 s92, v254, 23
	v_and_b32_e32 v184, 15, v12
	v_bfe_u32 v185, v12, 4, 2
	s_andn2_b64 vcc, exec, s[0:1]
	s_mov_b64 s[0:1], -1
	v_readlane_b32 s77, v254, 7
	v_readlane_b32 s75, v254, 10
	v_readlane_b32 s81, v254, 22
	s_movk_i32 s79, 0x5000
	s_mov_b32 s82, 0x1400000
	s_mov_b32 s83, 0x1800000
	s_mov_b32 s84, 0x1c00000
	s_mov_b32 s85, 0xf800000
	s_movk_i32 s86, 0x1000
	s_movk_i32 s87, 0x48
	s_movk_i32 s88, 0x1600
	s_mov_b64 s[90:91], 0x1000
	v_readlane_b32 s93, v254, 24
	s_cbranch_vccz .LBB0_401
	s_waitcnt vmcnt(0)
	v_lshl_or_b32 v14, s33, 6, v184
	s_lshl_b32 s100, s20, 8
	s_lshl_b32 s101, s38, 5
	s_or_b32 s100, s100, s101
	v_lshl_or_b32 v225, v185, 2, s100
	v_lshlrev_b32_e32 v222, 2, v225
	s_lshl_b32 s100, s22, 8
	v_add_u32_e32 v12, s100, v14
	v_lshl_add_u32 v12, v12, 10, v225
	v_lshlrev_b32_e32 v220, 2, v12
	v_mov_b32_e32 v224, v220
	v_lshlrev_b32_e32 v221, 2, v14
	s_lshl_b32 s100, s38, 4
	v_lshl_add_u32 v223, v14, 6, s100
	v_lshl_add_u32 v223, v185, 2, v223
	s_lshr_b32 s100, s22, 3
	s_mul_i32 s100, s100, 0x9000
	s_add_u32 s100, s45, s100
	s_addc_u32 s101, s68, 0
	global_load_dwordx4 v[140:143], v222, s[100:101]
	global_load_dwordx4 v[144:147], v222, s[100:101] offset:64
	global_load_dwordx4 v[148:151], v222, s[100:101] offset:512
	global_load_dwordx4 v[152:155], v222, s[100:101] offset:576
	global_load_dwordx4 v[156:159], v224, s[12:13]
	global_load_dwordx4 v[160:163], v224, s[12:13] offset:64
	global_load_dwordx4 v[164:167], v224, s[12:13] offset:512
	global_load_dwordx4 v[168:171], v224, s[12:13] offset:576
	v_add_u32_e32 v224, 0x10000, v224
	global_load_dwordx4 v[172:175], v224, s[12:13]
	global_load_dwordx4 v[176:179], v224, s[12:13] offset:64
	global_load_dwordx4 v[180:183], v224, s[12:13] offset:512
	global_load_dwordx4 v[184:187], v224, s[12:13] offset:576
	v_add_u32_e32 v224, 0x10000, v224
	global_load_dwordx4 v[188:191], v224, s[12:13]
	global_load_dwordx4 v[192:195], v224, s[12:13] offset:64
	global_load_dwordx4 v[196:199], v224, s[12:13] offset:512
	global_load_dwordx4 v[200:203], v224, s[12:13] offset:576
	v_add_u32_e32 v224, 0x10000, v224
	global_load_dwordx4 v[204:207], v224, s[12:13]
	global_load_dwordx4 v[208:211], v224, s[12:13] offset:64
	global_load_dwordx4 v[212:215], v224, s[12:13] offset:512
	global_load_dwordx4 v[228:231], v224, s[12:13] offset:576
	v_add_u32_e32 v224, 0x50000, v224
	s_waitcnt vmcnt(12)
	v_pk_mul_f32 v[140:141], v[140:141], 0.5 op_sel_hi:[1,0]
	v_pk_mul_f32 v[142:143], v[142:143], 0.5 op_sel_hi:[1,0]
	v_pk_mul_f32 v[144:145], v[144:145], 0.5 op_sel_hi:[1,0]
	v_pk_mul_f32 v[146:147], v[146:147], 0.5 op_sel_hi:[1,0]
	v_pk_mul_f32 v[148:149], v[148:149], 0.5 op_sel_hi:[1,0]
	v_pk_mul_f32 v[150:151], v[150:151], 0.5 op_sel_hi:[1,0]
	v_pk_mul_f32 v[152:153], v[152:153], 0.5 op_sel_hi:[1,0]
	v_pk_mul_f32 v[154:155], v[154:155], 0.5 op_sel_hi:[1,0]
	v_pk_fma_f32 v[128:129], v[128:129], v[140:141], v[156:157]
	v_pk_fma_f32 v[130:131], v[130:131], v[142:143], v[158:159]
	v_pk_fma_f32 v[124:125], v[124:125], v[144:145], v[160:161]
	v_pk_fma_f32 v[126:127], v[126:127], v[146:147], v[162:163]
	v_pk_fma_f32 v[120:121], v[120:121], v[148:149], v[164:165]
	v_pk_fma_f32 v[122:123], v[122:123], v[150:151], v[166:167]
	v_pk_fma_f32 v[116:117], v[116:117], v[152:153], v[168:169]
	v_pk_fma_f32 v[118:119], v[118:119], v[154:155], v[170:171]
	global_load_dwordx4 v[156:159], v224, s[12:13]
	global_load_dwordx4 v[160:163], v224, s[12:13] offset:64
	global_load_dwordx4 v[164:167], v224, s[12:13] offset:512
	global_load_dwordx4 v[168:171], v224, s[12:13] offset:576
	v_add_u32_e32 v224, 0x10000, v224
	v_mul_f32_e32 v132, v129, v129
	v_mul_f32_e32 v133, v131, v131
	v_fmac_f32_e32 v132, v128, v128
	v_fmac_f32_e32 v133, v130, v130
	v_add_f32_e32 v134, v132, v133
	v_mul_f32_e32 v132, v125, v125
	v_mul_f32_e32 v133, v127, v127
	v_fmac_f32_e32 v132, v124, v124
	v_fmac_f32_e32 v133, v126, v126
	v_add_f32_e32 v132, v132, v133
	v_add_f32_e32 v134, v134, v132
	v_mul_f32_e32 v132, v121, v121
	v_mul_f32_e32 v133, v123, v123
	v_fmac_f32_e32 v132, v120, v120
	v_fmac_f32_e32 v133, v122, v122
	v_add_f32_e32 v132, v132, v133
	v_add_f32_e32 v134, v134, v132
	v_mul_f32_e32 v132, v117, v117
	v_mul_f32_e32 v133, v119, v119
	v_fmac_f32_e32 v132, v116, v116
	v_fmac_f32_e32 v133, v118, v118
	v_add_f32_e32 v132, v132, v133
	v_add_f32_e32 v134, v134, v132
	ds_write_b32 v223, v134
	s_waitcnt vmcnt(12)
	v_pk_fma_f32 v[112:113], v[112:113], v[140:141], v[172:173]
	v_pk_fma_f32 v[114:115], v[114:115], v[142:143], v[174:175]
	v_pk_fma_f32 v[108:109], v[108:109], v[144:145], v[176:177]
	v_pk_fma_f32 v[110:111], v[110:111], v[146:147], v[178:179]
	v_pk_fma_f32 v[104:105], v[104:105], v[148:149], v[180:181]
	v_pk_fma_f32 v[106:107], v[106:107], v[150:151], v[182:183]
	v_pk_fma_f32 v[100:101], v[100:101], v[152:153], v[184:185]
	v_pk_fma_f32 v[102:103], v[102:103], v[154:155], v[186:187]
	global_load_dwordx4 v[172:175], v224, s[12:13]
	global_load_dwordx4 v[176:179], v224, s[12:13] offset:64
	global_load_dwordx4 v[180:183], v224, s[12:13] offset:512
	global_load_dwordx4 v[184:187], v224, s[12:13] offset:576
	v_add_u32_e32 v224, 0x10000, v224
	v_mul_f32_e32 v132, v113, v113
	v_mul_f32_e32 v133, v115, v115
	v_fmac_f32_e32 v132, v112, v112
	v_fmac_f32_e32 v133, v114, v114
	v_add_f32_e32 v135, v132, v133
	v_mul_f32_e32 v132, v109, v109
	v_mul_f32_e32 v133, v111, v111
	v_fmac_f32_e32 v132, v108, v108
	v_fmac_f32_e32 v133, v110, v110
	v_add_f32_e32 v132, v132, v133
	v_add_f32_e32 v135, v135, v132
	v_mul_f32_e32 v132, v105, v105
	v_mul_f32_e32 v133, v107, v107
	v_fmac_f32_e32 v132, v104, v104
	v_fmac_f32_e32 v133, v106, v106
	v_add_f32_e32 v132, v132, v133
	v_add_f32_e32 v135, v135, v132
	v_mul_f32_e32 v132, v101, v101
	v_mul_f32_e32 v133, v103, v103
	v_fmac_f32_e32 v132, v100, v100
	v_fmac_f32_e32 v133, v102, v102
	v_add_f32_e32 v132, v132, v133
	v_add_f32_e32 v135, v135, v132
	ds_write_b32 v223, v135 offset:1024
	s_waitcnt vmcnt(12)
	v_pk_fma_f32 v[96:97], v[96:97], v[140:141], v[188:189]
	v_pk_fma_f32 v[98:99], v[98:99], v[142:143], v[190:191]
	v_pk_fma_f32 v[92:93], v[92:93], v[144:145], v[192:193]
	v_pk_fma_f32 v[94:95], v[94:95], v[146:147], v[194:195]
	v_pk_fma_f32 v[88:89], v[88:89], v[148:149], v[196:197]
	v_pk_fma_f32 v[90:91], v[90:91], v[150:151], v[198:199]
	v_pk_fma_f32 v[84:85], v[84:85], v[152:153], v[200:201]
	v_pk_fma_f32 v[86:87], v[86:87], v[154:155], v[202:203]
	global_load_dwordx4 v[188:191], v224, s[12:13]
	global_load_dwordx4 v[192:195], v224, s[12:13] offset:64
	global_load_dwordx4 v[196:199], v224, s[12:13] offset:512
	global_load_dwordx4 v[200:203], v224, s[12:13] offset:576
	v_add_u32_e32 v224, 0x10000, v224
	v_mul_f32_e32 v132, v97, v97
	v_mul_f32_e32 v133, v99, v99
	v_fmac_f32_e32 v132, v96, v96
	v_fmac_f32_e32 v133, v98, v98
	v_add_f32_e32 v134, v132, v133
	v_mul_f32_e32 v132, v93, v93
	v_mul_f32_e32 v133, v95, v95
	v_fmac_f32_e32 v132, v92, v92
	v_fmac_f32_e32 v133, v94, v94
	v_add_f32_e32 v132, v132, v133
	v_add_f32_e32 v134, v134, v132
	v_mul_f32_e32 v132, v89, v89
	v_mul_f32_e32 v133, v91, v91
	v_fmac_f32_e32 v132, v88, v88
	v_fmac_f32_e32 v133, v90, v90
	v_add_f32_e32 v132, v132, v133
	v_add_f32_e32 v134, v134, v132
	v_mul_f32_e32 v132, v85, v85
	v_mul_f32_e32 v133, v87, v87
	v_fmac_f32_e32 v132, v84, v84
	v_fmac_f32_e32 v133, v86, v86
	v_add_f32_e32 v132, v132, v133
	v_add_f32_e32 v134, v134, v132
	ds_write_b32 v223, v134 offset:2048
	s_waitcnt vmcnt(12)
	v_pk_fma_f32 v[80:81], v[80:81], v[140:141], v[204:205]
	v_pk_fma_f32 v[82:83], v[82:83], v[142:143], v[206:207]
	v_pk_fma_f32 v[76:77], v[76:77], v[144:145], v[208:209]
	v_pk_fma_f32 v[78:79], v[78:79], v[146:147], v[210:211]
	v_pk_fma_f32 v[72:73], v[72:73], v[148:149], v[212:213]
	v_pk_fma_f32 v[74:75], v[74:75], v[150:151], v[214:215]
	v_pk_fma_f32 v[68:69], v[68:69], v[152:153], v[228:229]
	v_pk_fma_f32 v[70:71], v[70:71], v[154:155], v[230:231]
	global_load_dwordx4 v[204:207], v224, s[12:13]
	global_load_dwordx4 v[208:211], v224, s[12:13] offset:64
	global_load_dwordx4 v[212:215], v224, s[12:13] offset:512
	global_load_dwordx4 v[228:231], v224, s[12:13] offset:576
	v_mul_f32_e32 v132, v81, v81
	v_mul_f32_e32 v133, v83, v83
	v_fmac_f32_e32 v132, v80, v80
	v_fmac_f32_e32 v133, v82, v82
	v_add_f32_e32 v135, v132, v133
	v_mul_f32_e32 v132, v77, v77
	v_mul_f32_e32 v133, v79, v79
	v_fmac_f32_e32 v132, v76, v76
	v_fmac_f32_e32 v133, v78, v78
	v_add_f32_e32 v132, v132, v133
	v_add_f32_e32 v135, v135, v132
	v_mul_f32_e32 v132, v73, v73
	v_mul_f32_e32 v133, v75, v75
	v_fmac_f32_e32 v132, v72, v72
	v_fmac_f32_e32 v133, v74, v74
	v_add_f32_e32 v132, v132, v133
	v_add_f32_e32 v135, v135, v132
	v_mul_f32_e32 v132, v69, v69
	v_mul_f32_e32 v133, v71, v71
	v_fmac_f32_e32 v132, v68, v68
	v_fmac_f32_e32 v133, v70, v70
	v_add_f32_e32 v132, v132, v133
	v_add_f32_e32 v135, v135, v132
	ds_write_b32 v223, v135 offset:3072
	s_waitcnt vmcnt(12)
	v_pk_fma_f32 v[64:65], v[64:65], v[140:141], v[156:157]
	v_pk_fma_f32 v[66:67], v[66:67], v[142:143], v[158:159]
	v_pk_fma_f32 v[60:61], v[60:61], v[144:145], v[160:161]
	v_pk_fma_f32 v[62:63], v[62:63], v[146:147], v[162:163]
	v_pk_fma_f32 v[56:57], v[56:57], v[148:149], v[164:165]
	v_pk_fma_f32 v[58:59], v[58:59], v[150:151], v[166:167]
	v_pk_fma_f32 v[52:53], v[52:53], v[152:153], v[168:169]
	v_pk_fma_f32 v[54:55], v[54:55], v[154:155], v[170:171]
	v_mul_f32_e32 v132, v65, v65
	v_mul_f32_e32 v133, v67, v67
	v_fmac_f32_e32 v132, v64, v64
	v_fmac_f32_e32 v133, v66, v66
	v_add_f32_e32 v134, v132, v133
	v_mul_f32_e32 v132, v61, v61
	v_mul_f32_e32 v133, v63, v63
	v_fmac_f32_e32 v132, v60, v60
	v_fmac_f32_e32 v133, v62, v62
	v_add_f32_e32 v132, v132, v133
	v_add_f32_e32 v134, v134, v132
	v_mul_f32_e32 v132, v57, v57
	v_mul_f32_e32 v133, v59, v59
	v_fmac_f32_e32 v132, v56, v56
	v_fmac_f32_e32 v133, v58, v58
	v_add_f32_e32 v132, v132, v133
	v_add_f32_e32 v134, v134, v132
	v_mul_f32_e32 v132, v53, v53
	v_mul_f32_e32 v133, v55, v55
	v_fmac_f32_e32 v132, v52, v52
	v_fmac_f32_e32 v133, v54, v54
	v_add_f32_e32 v132, v132, v133
	v_add_f32_e32 v134, v134, v132
	ds_write_b32 v223, v134 offset:8192
	s_waitcnt vmcnt(8)
	v_pk_fma_f32 v[48:49], v[48:49], v[140:141], v[172:173]
	v_pk_fma_f32 v[50:51], v[50:51], v[142:143], v[174:175]
	v_pk_fma_f32 v[44:45], v[44:45], v[144:145], v[176:177]
	v_pk_fma_f32 v[46:47], v[46:47], v[146:147], v[178:179]
	v_pk_fma_f32 v[40:41], v[40:41], v[148:149], v[180:181]
	v_pk_fma_f32 v[42:43], v[42:43], v[150:151], v[182:183]
	v_pk_fma_f32 v[36:37], v[36:37], v[152:153], v[184:185]
	v_pk_fma_f32 v[38:39], v[38:39], v[154:155], v[186:187]
	v_mul_f32_e32 v132, v49, v49
	v_mul_f32_e32 v133, v51, v51
	v_fmac_f32_e32 v132, v48, v48
	v_fmac_f32_e32 v133, v50, v50
	v_add_f32_e32 v135, v132, v133
	v_mul_f32_e32 v132, v45, v45
	v_mul_f32_e32 v133, v47, v47
	v_fmac_f32_e32 v132, v44, v44
	v_fmac_f32_e32 v133, v46, v46
	v_add_f32_e32 v132, v132, v133
	v_add_f32_e32 v135, v135, v132
	v_mul_f32_e32 v132, v41, v41
	v_mul_f32_e32 v133, v43, v43
	v_fmac_f32_e32 v132, v40, v40
	v_fmac_f32_e32 v133, v42, v42
	v_add_f32_e32 v132, v132, v133
	v_add_f32_e32 v135, v135, v132
	v_mul_f32_e32 v132, v37, v37
	v_mul_f32_e32 v133, v39, v39
	v_fmac_f32_e32 v132, v36, v36
	v_fmac_f32_e32 v133, v38, v38
	v_add_f32_e32 v132, v132, v133
	v_add_f32_e32 v135, v135, v132
	ds_write_b32 v223, v135 offset:9216
	s_waitcnt vmcnt(4)
	v_pk_fma_f32 v[32:33], v[32:33], v[140:141], v[188:189]
	v_pk_fma_f32 v[34:35], v[34:35], v[142:143], v[190:191]
	v_pk_fma_f32 v[28:29], v[28:29], v[144:145], v[192:193]
	v_pk_fma_f32 v[30:31], v[30:31], v[146:147], v[194:195]
	v_pk_fma_f32 v[24:25], v[24:25], v[148:149], v[196:197]
	v_pk_fma_f32 v[26:27], v[26:27], v[150:151], v[198:199]
	v_pk_fma_f32 v[20:21], v[20:21], v[152:153], v[200:201]
	v_pk_fma_f32 v[22:23], v[22:23], v[154:155], v[202:203]
	v_mul_f32_e32 v132, v33, v33
	v_mul_f32_e32 v133, v35, v35
	v_fmac_f32_e32 v132, v32, v32
	v_fmac_f32_e32 v133, v34, v34
	v_add_f32_e32 v134, v132, v133
	v_mul_f32_e32 v132, v29, v29
	v_mul_f32_e32 v133, v31, v31
	v_fmac_f32_e32 v132, v28, v28
	v_fmac_f32_e32 v133, v30, v30
	v_add_f32_e32 v132, v132, v133
	v_add_f32_e32 v134, v134, v132
	v_mul_f32_e32 v132, v25, v25
	v_mul_f32_e32 v133, v27, v27
	v_fmac_f32_e32 v132, v24, v24
	v_fmac_f32_e32 v133, v26, v26
	v_add_f32_e32 v132, v132, v133
	v_add_f32_e32 v134, v134, v132
	v_mul_f32_e32 v132, v21, v21
	v_mul_f32_e32 v133, v23, v23
	v_fmac_f32_e32 v132, v20, v20
	v_fmac_f32_e32 v133, v22, v22
	v_add_f32_e32 v132, v132, v133
	v_add_f32_e32 v134, v134, v132
	ds_write_b32 v223, v134 offset:10240
	s_waitcnt vmcnt(0)
	v_pk_fma_f32 v[16:17], v[16:17], v[140:141], v[204:205]
	v_pk_fma_f32 v[18:19], v[18:19], v[142:143], v[206:207]
	v_pk_fma_f32 v[8:9], v[8:9], v[144:145], v[208:209]
	v_pk_fma_f32 v[10:11], v[10:11], v[146:147], v[210:211]
	v_pk_fma_f32 v[4:5], v[4:5], v[148:149], v[212:213]
	v_pk_fma_f32 v[6:7], v[6:7], v[150:151], v[214:215]
	v_pk_fma_f32 v[0:1], v[0:1], v[152:153], v[228:229]
	v_pk_fma_f32 v[2:3], v[2:3], v[154:155], v[230:231]
	v_mul_f32_e32 v132, v17, v17
	v_mul_f32_e32 v133, v19, v19
	v_fmac_f32_e32 v132, v16, v16
	v_fmac_f32_e32 v133, v18, v18
	v_add_f32_e32 v135, v132, v133
	v_mul_f32_e32 v132, v9, v9
	v_mul_f32_e32 v133, v11, v11
	v_fmac_f32_e32 v132, v8, v8
	v_fmac_f32_e32 v133, v10, v10
	v_add_f32_e32 v132, v132, v133
	v_add_f32_e32 v135, v135, v132
	v_mul_f32_e32 v132, v5, v5
	v_mul_f32_e32 v133, v7, v7
	v_fmac_f32_e32 v132, v4, v4
	v_fmac_f32_e32 v133, v6, v6
	v_add_f32_e32 v132, v132, v133
	v_add_f32_e32 v135, v135, v132
	v_mul_f32_e32 v132, v1, v1
	v_mul_f32_e32 v133, v3, v3
	v_fmac_f32_e32 v132, v0, v0
	v_fmac_f32_e32 v133, v2, v2
	v_add_f32_e32 v132, v132, v133
	v_add_f32_e32 v135, v135, v132
	ds_write_b32 v223, v135 offset:11264
	v_and_b32_e32 v15, 63, v216
	s_add_u32 s30, s30, 0x11200000
	s_addc_u32 s31, s31, 0
	s_waitcnt lgkmcnt(0)
	s_barrier
	s_and_b32 s0, s23, 0xffffffc0
	v_or_b32_e32 v12, s0, v15
	s_movk_i32 s0, 0x100
	v_cmp_gt_i32_e64 s[0:1], s0, v12
	s_waitcnt lgkmcnt(0)
	v_lshl_add_u32 v132, s22, 8, v12
	s_and_saveexec_b64 s[36:37], s[0:1]
	s_cbranch_execz .LBB0_381
	v_lshl_add_u32 v133, v12, 6, 0
	ds_read_b128 v[140:143], v133
	ds_read_b128 v[144:147], v133 offset:16
	ds_read_b128 v[148:151], v133 offset:32
	ds_read_b128 v[152:155], v133 offset:48
	v_ashrrev_i32_e32 v133, 31, v132
	s_ashr_i32 s21, s20, 31
	s_waitcnt lgkmcnt(0)
	v_add_f32_e32 v140, v140, v141
	v_add_f32_e32 v142, v142, v143
	v_add_f32_e32 v134, v140, v142
	v_add_f32_e32 v144, v144, v145
	v_add_f32_e32 v146, v146, v147
	v_add_f32_e32 v135, v144, v146
	v_add_f32_e32 v148, v148, v149
	v_add_f32_e32 v150, v150, v151
	v_add_f32_e32 v136, v148, v150
	v_add_f32_e32 v152, v152, v153
	v_add_f32_e32 v154, v154, v155
	v_add_f32_e32 v137, v152, v154
	v_mov_b32_e32 v138, v135
	v_mov_b32_e32 v139, v136
	v_mov_b32_e32 v135, v137
	v_pk_add_f32 v[134:135], v[138:139], v[134:135]
	v_lshl_add_u64 v[136:137], v[132:133], 4, s[30:31]
	v_pk_add_f32 v[134:135], v[134:135], v[134:135] op_sel:[0,1] op_sel_hi:[1,0]
	v_lshl_add_u64 v[136:137], s[20:21], 2, v[136:137]
	global_store_dword v[136:137], v134, off sc1

.LBB0_384:
	s_or_b64 exec, exec, s[28:29]
	s_and_b64 vcc, exec, s[10:11]
	s_cbranch_vccz .Lepi_skip_ystore_down
	v_mov_b32_e32 v224, v220
	global_store_dwordx4 v224, v[128:131], s[16:17]
	global_store_dwordx4 v224, v[124:127], s[16:17] offset:64
	global_store_dwordx4 v224, v[120:123], s[16:17] offset:512
	global_store_dwordx4 v224, v[116:119], s[16:17] offset:576
	v_add_u32_e32 v224, 0x10000, v224
	global_store_dwordx4 v224, v[112:115], s[16:17]
	global_store_dwordx4 v224, v[108:111], s[16:17] offset:64
	global_store_dwordx4 v224, v[104:107], s[16:17] offset:512
	global_store_dwordx4 v224, v[100:103], s[16:17] offset:576
	v_add_u32_e32 v224, 0x10000, v224
	global_store_dwordx4 v224, v[96:99], s[16:17]
	global_store_dwordx4 v224, v[92:95], s[16:17] offset:64
	global_store_dwordx4 v224, v[88:91], s[16:17] offset:512
	global_store_dwordx4 v224, v[84:87], s[16:17] offset:576
	v_add_u32_e32 v224, 0x10000, v224
	global_store_dwordx4 v224, v[80:83], s[16:17]
	global_store_dwordx4 v224, v[76:79], s[16:17] offset:64
	global_store_dwordx4 v224, v[72:75], s[16:17] offset:512
	global_store_dwordx4 v224, v[68:71], s[16:17] offset:576
	v_add_u32_e32 v224, 0x50000, v224
	global_store_dwordx4 v224, v[64:67], s[16:17]
	global_store_dwordx4 v224, v[60:63], s[16:17] offset:64
	global_store_dwordx4 v224, v[56:59], s[16:17] offset:512
	global_store_dwordx4 v224, v[52:55], s[16:17] offset:576
	v_add_u32_e32 v224, 0x10000, v224
	global_store_dwordx4 v224, v[48:51], s[16:17]
	global_store_dwordx4 v224, v[44:47], s[16:17] offset:64
	global_store_dwordx4 v224, v[40:43], s[16:17] offset:512
	global_store_dwordx4 v224, v[36:39], s[16:17] offset:576
	v_add_u32_e32 v224, 0x10000, v224
	global_store_dwordx4 v224, v[32:35], s[16:17]
	global_store_dwordx4 v224, v[28:31], s[16:17] offset:64
	global_store_dwordx4 v224, v[24:27], s[16:17] offset:512
	global_store_dwordx4 v224, v[20:23], s[16:17] offset:576
	v_add_u32_e32 v224, 0x10000, v224
	global_store_dwordx4 v224, v[16:19], s[16:17]
	global_store_dwordx4 v224, v[8:11], s[16:17] offset:64
	global_store_dwordx4 v224, v[4:7], s[16:17] offset:512
	global_store_dwordx4 v224, v[0:3], s[16:17] offset:576
.Lepi_skip_ystore_down:
	s_lshr_b32 s100, s22, 3
	s_mul_i32 s100, s100, 0x9000
	s_and_b64 vcc, exec, s[10:11]
	s_cselect_b32 s100, s100, 0
	s_cselect_b32 s101, 0x1000, 0
	v_add_u32_e32 v225, s101, v222
	s_add_u32 s100, s24, s100
	s_addc_u32 s101, s25, 0
	global_load_dwordx4 v[156:159], v222, s[100:101]
	global_load_dwordx4 v[160:163], v222, s[100:101] offset:64
	global_load_dwordx4 v[164:167], v222, s[100:101] offset:512
	global_load_dwordx4 v[168:171], v222, s[100:101] offset:576
	global_load_dwordx4 v[172:175], v225, s[100:101]
	global_load_dwordx4 v[176:179], v225, s[100:101] offset:64
	global_load_dwordx4 v[180:183], v225, s[100:101] offset:512
	global_load_dwordx4 v[184:187], v225, s[100:101] offset:576
	s_cmp_gt_u32 s23, 63
	s_cbranch_scc1 .LBB0_394
	s_lshl_b32 s8, s22, 4
	s_ashr_i32 s9, s8, 31
	s_lshl_b64 s[8:9], s[8:9], 2
	s_add_u32 s28, s21, s8
	s_addc_u32 s29, s39, s9
	s_mov_b32 s21, 0x400001
	s_branch .LBB0_387

.LBB0_394:
	s_waitcnt vmcnt(0) lgkmcnt(0)
	s_barrier
	s_and_saveexec_b64 s[28:29], s[0:1]
	s_cbranch_execz .LBB0_396
	v_ashrrev_i32_e32 v133, 31, v132
	v_lshl_add_u64 v[132:133], v[132:133], 4, s[30:31]
	global_load_dword v15, v[132:133], off sc1
	global_load_dword v134, v[132:133], off offset:4 sc1
	global_load_dword v135, v[132:133], off offset:8 sc1
	s_nop 0
	global_load_dword v132, v[132:133], off offset:12 sc1
	v_lshl_add_u32 v12, v12, 2, 0
	s_waitcnt vmcnt(3)
	v_add_f32_e32 v15, 0, v15
	s_waitcnt vmcnt(2)
	v_add_f32_e32 v15, v15, v134
	s_waitcnt vmcnt(1)
	v_add_f32_e32 v15, v15, v135
	s_waitcnt vmcnt(0)
	v_add_f32_e32 v15, v15, v132
	v_fmamk_f32 v15, v15, 0x3a800000, v218
	v_mul_f32_e32 v132, 0x4f800000, v15
	v_cmp_gt_f32_e32 vcc, s85, v15
	s_nop 1
	v_cndmask_b32_e32 v15, v15, v132, vcc
	v_sqrt_f32_e32 v132, v15
	s_nop 0
	v_add_u32_e32 v133, -1, v132
	v_add_u32_e32 v134, 1, v132
	v_fma_f32 v135, -v133, v132, v15
	v_fma_f32 v136, -v134, v132, v15
	v_cmp_ge_f32_e64 s[0:1], 0, v135
	s_nop 1
	v_cndmask_b32_e64 v132, v132, v133, s[0:1]
	v_cmp_lt_f32_e64 s[0:1], 0, v136
	s_nop 1
	v_cndmask_b32_e64 v132, v132, v134, s[0:1]
	v_mul_f32_e32 v133, 0x37800000, v132
	v_cndmask_b32_e32 v132, v132, v133, vcc
	v_cmp_class_f32_e32 vcc, v15, v219
	s_nop 1
	v_cndmask_b32_e32 v15, v132, v15, vcc
	v_div_scale_f32 v132, s[0:1], v15, v15, 1.0
	v_rcp_f32_e32 v133, v132
	v_div_scale_f32 v134, vcc, 1.0, v15, 1.0
	v_fma_f32 v135, -v132, v133, 1.0
	v_fmac_f32_e32 v133, v135, v133
	v_mul_f32_e32 v135, v134, v133
	v_fma_f32 v136, -v132, v135, v134
	v_fmac_f32_e32 v135, v136, v133
	v_fma_f32 v132, -v132, v135, v134
	v_div_fmas_f32 v132, v132, v133, v135
	v_div_fixup_f32 v15, v132, v15, 1.0
	ds_write_b32 v12, v15 offset:16384
.LBB0_396:
	s_or_b64 exec, exec, s[28:29]
	s_ashr_i32 s23, s22, 31
	s_lshl_b64 s[0:1], s[22:23], 20
	s_add_u32 s8, s16, s0
	s_waitcnt vmcnt(0) lgkmcnt(0)
	s_barrier
	s_addc_u32 s9, s17, s1
	ds_read_b32 v188, v221 offset:16384
	ds_read_b32 v190, v221 offset:16448
	ds_read_b32 v192, v221 offset:16512
	ds_read_b32 v194, v221 offset:16576
	ds_read_b32 v196, v221 offset:16896
	ds_read_b32 v198, v221 offset:16960
	ds_read_b32 v200, v221 offset:17024
	ds_read_b32 v202, v221 offset:17088
	s_and_b64 vcc, exec, s[10:11]
	s_cbranch_vccz .Lepi_final_down
	s_add_u32 s100, s26, 0x3100000
	s_addc_u32 s101, s27, 0
	v_lshrrev_b32_e32 v224, 1, v220
	v_pk_add_f32 v[172:173], v[172:173], 1.0 op_sel_hi:[1,0]
	v_pk_add_f32 v[174:175], v[174:175], 1.0 op_sel_hi:[1,0]
	v_pk_add_f32 v[176:177], v[176:177], 1.0 op_sel_hi:[1,0]
	v_pk_add_f32 v[178:179], v[178:179], 1.0 op_sel_hi:[1,0]
	v_pk_add_f32 v[180:181], v[180:181], 1.0 op_sel_hi:[1,0]
	v_pk_add_f32 v[182:183], v[182:183], 1.0 op_sel_hi:[1,0]
	v_pk_add_f32 v[184:185], v[184:185], 1.0 op_sel_hi:[1,0]
	v_pk_add_f32 v[186:187], v[186:187], 1.0 op_sel_hi:[1,0]
	s_waitcnt lgkmcnt(0)
	v_pk_mul_f32 v[132:133], v[128:129], v[188:189] op_sel_hi:[1,0]
	v_pk_mul_f32 v[134:135], v[130:131], v[188:189] op_sel_hi:[1,0]
	v_pk_fma_f32 v[132:133], v[172:173], v[132:133], v[156:157]
	v_pk_fma_f32 v[134:135], v[174:175], v[134:135], v[158:159]
	v_cvt_pk_bf16_f32 v132, v132, v133
	v_cvt_pk_bf16_f32 v133, v134, v135
	global_store_dwordx2 v224, v[132:133], s[100:101]
	v_pk_mul_f32 v[136:137], v[124:125], v[188:189] op_sel_hi:[1,0]
	v_pk_mul_f32 v[138:139], v[126:127], v[188:189] op_sel_hi:[1,0]
	v_pk_fma_f32 v[136:137], v[176:177], v[136:137], v[160:161]
	v_pk_fma_f32 v[138:139], v[178:179], v[138:139], v[162:163]
	v_cvt_pk_bf16_f32 v136, v136, v137
	v_cvt_pk_bf16_f32 v137, v138, v139
	global_store_dwordx2 v224, v[136:137], s[100:101] offset:32
	v_pk_mul_f32 v[140:141], v[120:121], v[188:189] op_sel_hi:[1,0]
	v_pk_mul_f32 v[142:143], v[122:123], v[188:189] op_sel_hi:[1,0]
	v_pk_fma_f32 v[140:141], v[180:181], v[140:141], v[164:165]
	v_pk_fma_f32 v[142:143], v[182:183], v[142:143], v[166:167]
	v_cvt_pk_bf16_f32 v140, v140, v141
	v_cvt_pk_bf16_f32 v141, v142, v143
	global_store_dwordx2 v224, v[140:141], s[100:101] offset:256
	v_pk_mul_f32 v[144:145], v[116:117], v[188:189] op_sel_hi:[1,0]
	v_pk_mul_f32 v[146:147], v[118:119], v[188:189] op_sel_hi:[1,0]
	v_pk_fma_f32 v[144:145], v[184:185], v[144:145], v[168:169]
	v_pk_fma_f32 v[146:147], v[186:187], v[146:147], v[170:171]
	v_cvt_pk_bf16_f32 v144, v144, v145
	v_cvt_pk_bf16_f32 v145, v146, v147
	global_store_dwordx2 v224, v[144:145], s[100:101] offset:288
	v_add_u32_e32 v224, 0x8000, v224
	v_pk_mul_f32 v[132:133], v[112:113], v[190:191] op_sel_hi:[1,0]
	v_pk_mul_f32 v[134:135], v[114:115], v[190:191] op_sel_hi:[1,0]
	v_pk_fma_f32 v[132:133], v[172:173], v[132:133], v[156:157]
	v_pk_fma_f32 v[134:135], v[174:175], v[134:135], v[158:159]
	v_cvt_pk_bf16_f32 v132, v132, v133
	v_cvt_pk_bf16_f32 v133, v134, v135
	global_store_dwordx2 v224, v[132:133], s[100:101]
	v_pk_mul_f32 v[136:137], v[108:109], v[190:191] op_sel_hi:[1,0]
	v_pk_mul_f32 v[138:139], v[110:111], v[190:191] op_sel_hi:[1,0]
	v_pk_fma_f32 v[136:137], v[176:177], v[136:137], v[160:161]
	v_pk_fma_f32 v[138:139], v[178:179], v[138:139], v[162:163]
	v_cvt_pk_bf16_f32 v136, v136, v137
	v_cvt_pk_bf16_f32 v137, v138, v139
	global_store_dwordx2 v224, v[136:137], s[100:101] offset:32
	v_pk_mul_f32 v[140:141], v[104:105], v[190:191] op_sel_hi:[1,0]
	v_pk_mul_f32 v[142:143], v[106:107], v[190:191] op_sel_hi:[1,0]
	v_pk_fma_f32 v[140:141], v[180:181], v[140:141], v[164:165]
	v_pk_fma_f32 v[142:143], v[182:183], v[142:143], v[166:167]
	v_cvt_pk_bf16_f32 v140, v140, v141
	v_cvt_pk_bf16_f32 v141, v142, v143
	global_store_dwordx2 v224, v[140:141], s[100:101] offset:256
	v_pk_mul_f32 v[144:145], v[100:101], v[190:191] op_sel_hi:[1,0]
	v_pk_mul_f32 v[146:147], v[102:103], v[190:191] op_sel_hi:[1,0]
	v_pk_fma_f32 v[144:145], v[184:185], v[144:145], v[168:169]
	v_pk_fma_f32 v[146:147], v[186:187], v[146:147], v[170:171]
	v_cvt_pk_bf16_f32 v144, v144, v145
	v_cvt_pk_bf16_f32 v145, v146, v147
	global_store_dwordx2 v224, v[144:145], s[100:101] offset:288
	v_add_u32_e32 v224, 0x8000, v224
	v_pk_mul_f32 v[132:133], v[96:97], v[192:193] op_sel_hi:[1,0]
	v_pk_mul_f32 v[134:135], v[98:99], v[192:193] op_sel_hi:[1,0]
	v_pk_fma_f32 v[132:133], v[172:173], v[132:133], v[156:157]
	v_pk_fma_f32 v[134:135], v[174:175], v[134:135], v[158:159]
	v_cvt_pk_bf16_f32 v132, v132, v133
	v_cvt_pk_bf16_f32 v133, v134, v135
	global_store_dwordx2 v224, v[132:133], s[100:101]
	v_pk_mul_f32 v[136:137], v[92:93], v[192:193] op_sel_hi:[1,0]
	v_pk_mul_f32 v[138:139], v[94:95], v[192:193] op_sel_hi:[1,0]
	v_pk_fma_f32 v[136:137], v[176:177], v[136:137], v[160:161]
	v_pk_fma_f32 v[138:139], v[178:179], v[138:139], v[162:163]
	v_cvt_pk_bf16_f32 v136, v136, v137
	v_cvt_pk_bf16_f32 v137, v138, v139
	global_store_dwordx2 v224, v[136:137], s[100:101] offset:32
	v_pk_mul_f32 v[140:141], v[88:89], v[192:193] op_sel_hi:[1,0]
	v_pk_mul_f32 v[142:143], v[90:91], v[192:193] op_sel_hi:[1,0]
	v_pk_fma_f32 v[140:141], v[180:181], v[140:141], v[164:165]
	v_pk_fma_f32 v[142:143], v[182:183], v[142:143], v[166:167]
	v_cvt_pk_bf16_f32 v140, v140, v141
	v_cvt_pk_bf16_f32 v141, v142, v143
	global_store_dwordx2 v224, v[140:141], s[100:101] offset:256
	v_pk_mul_f32 v[144:145], v[84:85], v[192:193] op_sel_hi:[1,0]
	v_pk_mul_f32 v[146:147], v[86:87], v[192:193] op_sel_hi:[1,0]
	v_pk_fma_f32 v[144:145], v[184:185], v[144:145], v[168:169]
	v_pk_fma_f32 v[146:147], v[186:187], v[146:147], v[170:171]
	v_cvt_pk_bf16_f32 v144, v144, v145
	v_cvt_pk_bf16_f32 v145, v146, v147
	global_store_dwordx2 v224, v[144:145], s[100:101] offset:288
	v_add_u32_e32 v224, 0x8000, v224
	v_pk_mul_f32 v[132:133], v[80:81], v[194:195] op_sel_hi:[1,0]
	v_pk_mul_f32 v[134:135], v[82:83], v[194:195] op_sel_hi:[1,0]
	v_pk_fma_f32 v[132:133], v[172:173], v[132:133], v[156:157]
	v_pk_fma_f32 v[134:135], v[174:175], v[134:135], v[158:159]
	v_cvt_pk_bf16_f32 v132, v132, v133
	v_cvt_pk_bf16_f32 v133, v134, v135
	global_store_dwordx2 v224, v[132:133], s[100:101]
	v_pk_mul_f32 v[136:137], v[76:77], v[194:195] op_sel_hi:[1,0]
	v_pk_mul_f32 v[138:139], v[78:79], v[194:195] op_sel_hi:[1,0]
	v_pk_fma_f32 v[136:137], v[176:177], v[136:137], v[160:161]
	v_pk_fma_f32 v[138:139], v[178:179], v[138:139], v[162:163]
	v_cvt_pk_bf16_f32 v136, v136, v137
	v_cvt_pk_bf16_f32 v137, v138, v139
	global_store_dwordx2 v224, v[136:137], s[100:101] offset:32
	v_pk_mul_f32 v[140:141], v[72:73], v[194:195] op_sel_hi:[1,0]
	v_pk_mul_f32 v[142:143], v[74:75], v[194:195] op_sel_hi:[1,0]
	v_pk_fma_f32 v[140:141], v[180:181], v[140:141], v[164:165]
	v_pk_fma_f32 v[142:143], v[182:183], v[142:143], v[166:167]
	v_cvt_pk_bf16_f32 v140, v140, v141
	v_cvt_pk_bf16_f32 v141, v142, v143
	global_store_dwordx2 v224, v[140:141], s[100:101] offset:256
	v_pk_mul_f32 v[144:145], v[68:69], v[194:195] op_sel_hi:[1,0]
	v_pk_mul_f32 v[146:147], v[70:71], v[194:195] op_sel_hi:[1,0]
	v_pk_fma_f32 v[144:145], v[184:185], v[144:145], v[168:169]
	v_pk_fma_f32 v[146:147], v[186:187], v[146:147], v[170:171]
	v_cvt_pk_bf16_f32 v144, v144, v145
	v_cvt_pk_bf16_f32 v145, v146, v147
	global_store_dwordx2 v224, v[144:145], s[100:101] offset:288
	v_add_u32_e32 v224, 0x28000, v224
	v_pk_mul_f32 v[132:133], v[64:65], v[196:197] op_sel_hi:[1,0]
	v_pk_mul_f32 v[134:135], v[66:67], v[196:197] op_sel_hi:[1,0]
	v_pk_fma_f32 v[132:133], v[172:173], v[132:133], v[156:157]
	v_pk_fma_f32 v[134:135], v[174:175], v[134:135], v[158:159]
	v_cvt_pk_bf16_f32 v132, v132, v133
	v_cvt_pk_bf16_f32 v133, v134, v135
	global_store_dwordx2 v224, v[132:133], s[100:101]
	v_pk_mul_f32 v[136:137], v[60:61], v[196:197] op_sel_hi:[1,0]
	v_pk_mul_f32 v[138:139], v[62:63], v[196:197] op_sel_hi:[1,0]
	v_pk_fma_f32 v[136:137], v[176:177], v[136:137], v[160:161]
	v_pk_fma_f32 v[138:139], v[178:179], v[138:139], v[162:163]
	v_cvt_pk_bf16_f32 v136, v136, v137
	v_cvt_pk_bf16_f32 v137, v138, v139
	global_store_dwordx2 v224, v[136:137], s[100:101] offset:32
	v_pk_mul_f32 v[140:141], v[56:57], v[196:197] op_sel_hi:[1,0]
	v_pk_mul_f32 v[142:143], v[58:59], v[196:197] op_sel_hi:[1,0]
	v_pk_fma_f32 v[140:141], v[180:181], v[140:141], v[164:165]
	v_pk_fma_f32 v[142:143], v[182:183], v[142:143], v[166:167]
	v_cvt_pk_bf16_f32 v140, v140, v141
	v_cvt_pk_bf16_f32 v141, v142, v143
	global_store_dwordx2 v224, v[140:141], s[100:101] offset:256
	v_pk_mul_f32 v[144:145], v[52:53], v[196:197] op_sel_hi:[1,0]
	v_pk_mul_f32 v[146:147], v[54:55], v[196:197] op_sel_hi:[1,0]
	v_pk_fma_f32 v[144:145], v[184:185], v[144:145], v[168:169]
	v_pk_fma_f32 v[146:147], v[186:187], v[146:147], v[170:171]
	v_cvt_pk_bf16_f32 v144, v144, v145
	v_cvt_pk_bf16_f32 v145, v146, v147
	global_store_dwordx2 v224, v[144:145], s[100:101] offset:288
	v_add_u32_e32 v224, 0x8000, v224
	v_pk_mul_f32 v[132:133], v[48:49], v[198:199] op_sel_hi:[1,0]
	v_pk_mul_f32 v[134:135], v[50:51], v[198:199] op_sel_hi:[1,0]
	v_pk_fma_f32 v[132:133], v[172:173], v[132:133], v[156:157]
	v_pk_fma_f32 v[134:135], v[174:175], v[134:135], v[158:159]
	v_cvt_pk_bf16_f32 v132, v132, v133
	v_cvt_pk_bf16_f32 v133, v134, v135
	global_store_dwordx2 v224, v[132:133], s[100:101]
	v_pk_mul_f32 v[136:137], v[44:45], v[198:199] op_sel_hi:[1,0]
	v_pk_mul_f32 v[138:139], v[46:47], v[198:199] op_sel_hi:[1,0]
	v_pk_fma_f32 v[136:137], v[176:177], v[136:137], v[160:161]
	v_pk_fma_f32 v[138:139], v[178:179], v[138:139], v[162:163]
	v_cvt_pk_bf16_f32 v136, v136, v137
	v_cvt_pk_bf16_f32 v137, v138, v139
	global_store_dwordx2 v224, v[136:137], s[100:101] offset:32
	v_pk_mul_f32 v[140:141], v[40:41], v[198:199] op_sel_hi:[1,0]
	v_pk_mul_f32 v[142:143], v[42:43], v[198:199] op_sel_hi:[1,0]
	v_pk_fma_f32 v[140:141], v[180:181], v[140:141], v[164:165]
	v_pk_fma_f32 v[142:143], v[182:183], v[142:143], v[166:167]
	v_cvt_pk_bf16_f32 v140, v140, v141
	v_cvt_pk_bf16_f32 v141, v142, v143
	global_store_dwordx2 v224, v[140:141], s[100:101] offset:256
	v_pk_mul_f32 v[144:145], v[36:37], v[198:199] op_sel_hi:[1,0]
	v_pk_mul_f32 v[146:147], v[38:39], v[198:199] op_sel_hi:[1,0]
	v_pk_fma_f32 v[144:145], v[184:185], v[144:145], v[168:169]
	v_pk_fma_f32 v[146:147], v[186:187], v[146:147], v[170:171]
	v_cvt_pk_bf16_f32 v144, v144, v145
	v_cvt_pk_bf16_f32 v145, v146, v147
	global_store_dwordx2 v224, v[144:145], s[100:101] offset:288
	v_add_u32_e32 v224, 0x8000, v224
	v_pk_mul_f32 v[132:133], v[32:33], v[200:201] op_sel_hi:[1,0]
	v_pk_mul_f32 v[134:135], v[34:35], v[200:201] op_sel_hi:[1,0]
	v_pk_fma_f32 v[132:133], v[172:173], v[132:133], v[156:157]
	v_pk_fma_f32 v[134:135], v[174:175], v[134:135], v[158:159]
	v_cvt_pk_bf16_f32 v132, v132, v133
	v_cvt_pk_bf16_f32 v133, v134, v135
	global_store_dwordx2 v224, v[132:133], s[100:101]
	v_pk_mul_f32 v[136:137], v[28:29], v[200:201] op_sel_hi:[1,0]
	v_pk_mul_f32 v[138:139], v[30:31], v[200:201] op_sel_hi:[1,0]
	v_pk_fma_f32 v[136:137], v[176:177], v[136:137], v[160:161]
	v_pk_fma_f32 v[138:139], v[178:179], v[138:139], v[162:163]
	v_cvt_pk_bf16_f32 v136, v136, v137
	v_cvt_pk_bf16_f32 v137, v138, v139
	global_store_dwordx2 v224, v[136:137], s[100:101] offset:32
	v_pk_mul_f32 v[140:141], v[24:25], v[200:201] op_sel_hi:[1,0]
	v_pk_mul_f32 v[142:143], v[26:27], v[200:201] op_sel_hi:[1,0]
	v_pk_fma_f32 v[140:141], v[180:181], v[140:141], v[164:165]
	v_pk_fma_f32 v[142:143], v[182:183], v[142:143], v[166:167]
	v_cvt_pk_bf16_f32 v140, v140, v141
	v_cvt_pk_bf16_f32 v141, v142, v143
	global_store_dwordx2 v224, v[140:141], s[100:101] offset:256
	v_pk_mul_f32 v[144:145], v[20:21], v[200:201] op_sel_hi:[1,0]
	v_pk_mul_f32 v[146:147], v[22:23], v[200:201] op_sel_hi:[1,0]
	v_pk_fma_f32 v[144:145], v[184:185], v[144:145], v[168:169]
	v_pk_fma_f32 v[146:147], v[186:187], v[146:147], v[170:171]
	v_cvt_pk_bf16_f32 v144, v144, v145
	v_cvt_pk_bf16_f32 v145, v146, v147
	global_store_dwordx2 v224, v[144:145], s[100:101] offset:288
	v_add_u32_e32 v224, 0x8000, v224
	v_pk_mul_f32 v[132:133], v[16:17], v[202:203] op_sel_hi:[1,0]
	v_pk_mul_f32 v[134:135], v[18:19], v[202:203] op_sel_hi:[1,0]
	v_pk_fma_f32 v[132:133], v[172:173], v[132:133], v[156:157]
	v_pk_fma_f32 v[134:135], v[174:175], v[134:135], v[158:159]
	v_cvt_pk_bf16_f32 v132, v132, v133
	v_cvt_pk_bf16_f32 v133, v134, v135
	global_store_dwordx2 v224, v[132:133], s[100:101]
	v_pk_mul_f32 v[136:137], v[8:9], v[202:203] op_sel_hi:[1,0]
	v_pk_mul_f32 v[138:139], v[10:11], v[202:203] op_sel_hi:[1,0]
	v_pk_fma_f32 v[136:137], v[176:177], v[136:137], v[160:161]
	v_pk_fma_f32 v[138:139], v[178:179], v[138:139], v[162:163]
	v_cvt_pk_bf16_f32 v136, v136, v137
	v_cvt_pk_bf16_f32 v137, v138, v139
	global_store_dwordx2 v224, v[136:137], s[100:101] offset:32
	v_pk_mul_f32 v[140:141], v[4:5], v[202:203] op_sel_hi:[1,0]
	v_pk_mul_f32 v[142:143], v[6:7], v[202:203] op_sel_hi:[1,0]
	v_pk_fma_f32 v[140:141], v[180:181], v[140:141], v[164:165]
	v_pk_fma_f32 v[142:143], v[182:183], v[142:143], v[166:167]
	v_cvt_pk_bf16_f32 v140, v140, v141
	v_cvt_pk_bf16_f32 v141, v142, v143
	global_store_dwordx2 v224, v[140:141], s[100:101] offset:256
	v_pk_mul_f32 v[144:145], v[0:1], v[202:203] op_sel_hi:[1,0]
	v_pk_mul_f32 v[146:147], v[2:3], v[202:203] op_sel_hi:[1,0]
	v_pk_fma_f32 v[144:145], v[184:185], v[144:145], v[168:169]
	v_pk_fma_f32 v[146:147], v[186:187], v[146:147], v[170:171]
	v_cvt_pk_bf16_f32 v144, v144, v145
	v_cvt_pk_bf16_f32 v145, v146, v147
	global_store_dwordx2 v224, v[144:145], s[100:101] offset:288
	s_branch .LBB0_400
.Lepi_final_down:
	v_mov_b32_e32 v224, v220
	s_waitcnt lgkmcnt(0)
	v_pk_mul_f32 v[132:133], v[128:129], v[188:189] op_sel_hi:[1,0]
	v_pk_mul_f32 v[134:135], v[130:131], v[188:189] op_sel_hi:[1,0]
	v_pk_mul_f32 v[132:133], v[156:157], v[132:133]
	v_pk_mul_f32 v[134:135], v[158:159], v[134:135]
	global_store_dwordx4 v224, v[132:135], s[16:17]
	v_pk_mul_f32 v[136:137], v[124:125], v[188:189] op_sel_hi:[1,0]
	v_pk_mul_f32 v[138:139], v[126:127], v[188:189] op_sel_hi:[1,0]
	v_pk_mul_f32 v[136:137], v[160:161], v[136:137]
	v_pk_mul_f32 v[138:139], v[162:163], v[138:139]
	global_store_dwordx4 v224, v[136:139], s[16:17] offset:64
	v_pk_mul_f32 v[140:141], v[120:121], v[188:189] op_sel_hi:[1,0]
	v_pk_mul_f32 v[142:143], v[122:123], v[188:189] op_sel_hi:[1,0]
	v_pk_mul_f32 v[140:141], v[164:165], v[140:141]
	v_pk_mul_f32 v[142:143], v[166:167], v[142:143]
	global_store_dwordx4 v224, v[140:143], s[16:17] offset:512
	v_pk_mul_f32 v[144:145], v[116:117], v[188:189] op_sel_hi:[1,0]
	v_pk_mul_f32 v[146:147], v[118:119], v[188:189] op_sel_hi:[1,0]
	v_pk_mul_f32 v[144:145], v[168:169], v[144:145]
	v_pk_mul_f32 v[146:147], v[170:171], v[146:147]
	global_store_dwordx4 v224, v[144:147], s[16:17] offset:576
	v_add_u32_e32 v224, 0x10000, v224
	v_pk_mul_f32 v[132:133], v[112:113], v[190:191] op_sel_hi:[1,0]
	v_pk_mul_f32 v[134:135], v[114:115], v[190:191] op_sel_hi:[1,0]
	v_pk_mul_f32 v[132:133], v[156:157], v[132:133]
	v_pk_mul_f32 v[134:135], v[158:159], v[134:135]
	global_store_dwordx4 v224, v[132:135], s[16:17]
	v_pk_mul_f32 v[136:137], v[108:109], v[190:191] op_sel_hi:[1,0]
	v_pk_mul_f32 v[138:139], v[110:111], v[190:191] op_sel_hi:[1,0]
	v_pk_mul_f32 v[136:137], v[160:161], v[136:137]
	v_pk_mul_f32 v[138:139], v[162:163], v[138:139]
	global_store_dwordx4 v224, v[136:139], s[16:17] offset:64
	v_pk_mul_f32 v[140:141], v[104:105], v[190:191] op_sel_hi:[1,0]
	v_pk_mul_f32 v[142:143], v[106:107], v[190:191] op_sel_hi:[1,0]
	v_pk_mul_f32 v[140:141], v[164:165], v[140:141]
	v_pk_mul_f32 v[142:143], v[166:167], v[142:143]
	global_store_dwordx4 v224, v[140:143], s[16:17] offset:512
	v_pk_mul_f32 v[144:145], v[100:101], v[190:191] op_sel_hi:[1,0]
	v_pk_mul_f32 v[146:147], v[102:103], v[190:191] op_sel_hi:[1,0]
	v_pk_mul_f32 v[144:145], v[168:169], v[144:145]
	v_pk_mul_f32 v[146:147], v[170:171], v[146:147]
	global_store_dwordx4 v224, v[144:147], s[16:17] offset:576
	v_add_u32_e32 v224, 0x10000, v224
	v_pk_mul_f32 v[132:133], v[96:97], v[192:193] op_sel_hi:[1,0]
	v_pk_mul_f32 v[134:135], v[98:99], v[192:193] op_sel_hi:[1,0]
	v_pk_mul_f32 v[132:133], v[156:157], v[132:133]
	v_pk_mul_f32 v[134:135], v[158:159], v[134:135]
	global_store_dwordx4 v224, v[132:135], s[16:17]
	v_pk_mul_f32 v[136:137], v[92:93], v[192:193] op_sel_hi:[1,0]
	v_pk_mul_f32 v[138:139], v[94:95], v[192:193] op_sel_hi:[1,0]
	v_pk_mul_f32 v[136:137], v[160:161], v[136:137]
	v_pk_mul_f32 v[138:139], v[162:163], v[138:139]
	global_store_dwordx4 v224, v[136:139], s[16:17] offset:64
	v_pk_mul_f32 v[140:141], v[88:89], v[192:193] op_sel_hi:[1,0]
	v_pk_mul_f32 v[142:143], v[90:91], v[192:193] op_sel_hi:[1,0]
	v_pk_mul_f32 v[140:141], v[164:165], v[140:141]
	v_pk_mul_f32 v[142:143], v[166:167], v[142:143]
	global_store_dwordx4 v224, v[140:143], s[16:17] offset:512
	v_pk_mul_f32 v[144:145], v[84:85], v[192:193] op_sel_hi:[1,0]
	v_pk_mul_f32 v[146:147], v[86:87], v[192:193] op_sel_hi:[1,0]
	v_pk_mul_f32 v[144:145], v[168:169], v[144:145]
	v_pk_mul_f32 v[146:147], v[170:171], v[146:147]
	global_store_dwordx4 v224, v[144:147], s[16:17] offset:576
	v_add_u32_e32 v224, 0x10000, v224
	v_pk_mul_f32 v[132:133], v[80:81], v[194:195] op_sel_hi:[1,0]
	v_pk_mul_f32 v[134:135], v[82:83], v[194:195] op_sel_hi:[1,0]
	v_pk_mul_f32 v[132:133], v[156:157], v[132:133]
	v_pk_mul_f32 v[134:135], v[158:159], v[134:135]
	global_store_dwordx4 v224, v[132:135], s[16:17]
	v_pk_mul_f32 v[136:137], v[76:77], v[194:195] op_sel_hi:[1,0]
	v_pk_mul_f32 v[138:139], v[78:79], v[194:195] op_sel_hi:[1,0]
	v_pk_mul_f32 v[136:137], v[160:161], v[136:137]
	v_pk_mul_f32 v[138:139], v[162:163], v[138:139]
	global_store_dwordx4 v224, v[136:139], s[16:17] offset:64
	v_pk_mul_f32 v[140:141], v[72:73], v[194:195] op_sel_hi:[1,0]
	v_pk_mul_f32 v[142:143], v[74:75], v[194:195] op_sel_hi:[1,0]
	v_pk_mul_f32 v[140:141], v[164:165], v[140:141]
	v_pk_mul_f32 v[142:143], v[166:167], v[142:143]
	global_store_dwordx4 v224, v[140:143], s[16:17] offset:512
	v_pk_mul_f32 v[144:145], v[68:69], v[194:195] op_sel_hi:[1,0]
	v_pk_mul_f32 v[146:147], v[70:71], v[194:195] op_sel_hi:[1,0]
	v_pk_mul_f32 v[144:145], v[168:169], v[144:145]
	v_pk_mul_f32 v[146:147], v[170:171], v[146:147]
	global_store_dwordx4 v224, v[144:147], s[16:17] offset:576
	v_add_u32_e32 v224, 0x50000, v224
	v_pk_mul_f32 v[132:133], v[64:65], v[196:197] op_sel_hi:[1,0]
	v_pk_mul_f32 v[134:135], v[66:67], v[196:197] op_sel_hi:[1,0]
	v_pk_mul_f32 v[132:133], v[156:157], v[132:133]
	v_pk_mul_f32 v[134:135], v[158:159], v[134:135]
	global_store_dwordx4 v224, v[132:135], s[16:17]
	v_pk_mul_f32 v[136:137], v[60:61], v[196:197] op_sel_hi:[1,0]
	v_pk_mul_f32 v[138:139], v[62:63], v[196:197] op_sel_hi:[1,0]
	v_pk_mul_f32 v[136:137], v[160:161], v[136:137]
	v_pk_mul_f32 v[138:139], v[162:163], v[138:139]
	global_store_dwordx4 v224, v[136:139], s[16:17] offset:64
	v_pk_mul_f32 v[140:141], v[56:57], v[196:197] op_sel_hi:[1,0]
	v_pk_mul_f32 v[142:143], v[58:59], v[196:197] op_sel_hi:[1,0]
	v_pk_mul_f32 v[140:141], v[164:165], v[140:141]
	v_pk_mul_f32 v[142:143], v[166:167], v[142:143]
	global_store_dwordx4 v224, v[140:143], s[16:17] offset:512
	v_pk_mul_f32 v[144:145], v[52:53], v[196:197] op_sel_hi:[1,0]
	v_pk_mul_f32 v[146:147], v[54:55], v[196:197] op_sel_hi:[1,0]
	v_pk_mul_f32 v[144:145], v[168:169], v[144:145]
	v_pk_mul_f32 v[146:147], v[170:171], v[146:147]
	global_store_dwordx4 v224, v[144:147], s[16:17] offset:576
	v_add_u32_e32 v224, 0x10000, v224
	v_pk_mul_f32 v[132:133], v[48:49], v[198:199] op_sel_hi:[1,0]
	v_pk_mul_f32 v[134:135], v[50:51], v[198:199] op_sel_hi:[1,0]
	v_pk_mul_f32 v[132:133], v[156:157], v[132:133]
	v_pk_mul_f32 v[134:135], v[158:159], v[134:135]
	global_store_dwordx4 v224, v[132:135], s[16:17]
	v_pk_mul_f32 v[136:137], v[44:45], v[198:199] op_sel_hi:[1,0]
	v_pk_mul_f32 v[138:139], v[46:47], v[198:199] op_sel_hi:[1,0]
	v_pk_mul_f32 v[136:137], v[160:161], v[136:137]
	v_pk_mul_f32 v[138:139], v[162:163], v[138:139]
	global_store_dwordx4 v224, v[136:139], s[16:17] offset:64
	v_pk_mul_f32 v[140:141], v[40:41], v[198:199] op_sel_hi:[1,0]
	v_pk_mul_f32 v[142:143], v[42:43], v[198:199] op_sel_hi:[1,0]
	v_pk_mul_f32 v[140:141], v[164:165], v[140:141]
	v_pk_mul_f32 v[142:143], v[166:167], v[142:143]
	global_store_dwordx4 v224, v[140:143], s[16:17] offset:512
	v_pk_mul_f32 v[144:145], v[36:37], v[198:199] op_sel_hi:[1,0]
	v_pk_mul_f32 v[146:147], v[38:39], v[198:199] op_sel_hi:[1,0]
	v_pk_mul_f32 v[144:145], v[168:169], v[144:145]
	v_pk_mul_f32 v[146:147], v[170:171], v[146:147]
	global_store_dwordx4 v224, v[144:147], s[16:17] offset:576
	v_add_u32_e32 v224, 0x10000, v224
	v_pk_mul_f32 v[132:133], v[32:33], v[200:201] op_sel_hi:[1,0]
	v_pk_mul_f32 v[134:135], v[34:35], v[200:201] op_sel_hi:[1,0]
	v_pk_mul_f32 v[132:133], v[156:157], v[132:133]
	v_pk_mul_f32 v[134:135], v[158:159], v[134:135]
	global_store_dwordx4 v224, v[132:135], s[16:17]
	v_pk_mul_f32 v[136:137], v[28:29], v[200:201] op_sel_hi:[1,0]
	v_pk_mul_f32 v[138:139], v[30:31], v[200:201] op_sel_hi:[1,0]
	v_pk_mul_f32 v[136:137], v[160:161], v[136:137]
	v_pk_mul_f32 v[138:139], v[162:163], v[138:139]
	global_store_dwordx4 v224, v[136:139], s[16:17] offset:64
	v_pk_mul_f32 v[140:141], v[24:25], v[200:201] op_sel_hi:[1,0]
	v_pk_mul_f32 v[142:143], v[26:27], v[200:201] op_sel_hi:[1,0]
	v_pk_mul_f32 v[140:141], v[164:165], v[140:141]
	v_pk_mul_f32 v[142:143], v[166:167], v[142:143]
	global_store_dwordx4 v224, v[140:143], s[16:17] offset:512
	v_pk_mul_f32 v[144:145], v[20:21], v[200:201] op_sel_hi:[1,0]
	v_pk_mul_f32 v[146:147], v[22:23], v[200:201] op_sel_hi:[1,0]
	v_pk_mul_f32 v[144:145], v[168:169], v[144:145]
	v_pk_mul_f32 v[146:147], v[170:171], v[146:147]
	global_store_dwordx4 v224, v[144:147], s[16:17] offset:576
	v_add_u32_e32 v224, 0x10000, v224
	v_pk_mul_f32 v[132:133], v[16:17], v[202:203] op_sel_hi:[1,0]
	v_pk_mul_f32 v[134:135], v[18:19], v[202:203] op_sel_hi:[1,0]
	v_pk_mul_f32 v[132:133], v[156:157], v[132:133]
	v_pk_mul_f32 v[134:135], v[158:159], v[134:135]
	global_store_dwordx4 v224, v[132:135], s[16:17]
	v_pk_mul_f32 v[136:137], v[8:9], v[202:203] op_sel_hi:[1,0]
	v_pk_mul_f32 v[138:139], v[10:11], v[202:203] op_sel_hi:[1,0]
	v_pk_mul_f32 v[136:137], v[160:161], v[136:137]
	v_pk_mul_f32 v[138:139], v[162:163], v[138:139]
	global_store_dwordx4 v224, v[136:139], s[16:17] offset:64
	v_pk_mul_f32 v[140:141], v[4:5], v[202:203] op_sel_hi:[1,0]
	v_pk_mul_f32 v[142:143], v[6:7], v[202:203] op_sel_hi:[1,0]
	v_pk_mul_f32 v[140:141], v[164:165], v[140:141]
	v_pk_mul_f32 v[142:143], v[166:167], v[142:143]
	global_store_dwordx4 v224, v[140:143], s[16:17] offset:512
	v_pk_mul_f32 v[144:145], v[0:1], v[202:203] op_sel_hi:[1,0]
	v_pk_mul_f32 v[146:147], v[2:3], v[202:203] op_sel_hi:[1,0]
	v_pk_mul_f32 v[144:145], v[168:169], v[144:145]
	v_pk_mul_f32 v[146:147], v[170:171], v[146:147]
	global_store_dwordx4 v224, v[144:147], s[16:17] offset:576
	s_branch .LBB0_400

.LBB0_935:
	v_mov_b32_e32 v12, v216
	s_cmpk_lg_i32 s70, 0x100
	s_waitcnt vmcnt(0)
	s_barrier
	s_cselect_b64 s[22:23], -1, 0
	v_readfirstlane_b32 s7, v12
	s_ashr_i32 s28, s7, 8
	s_bfe_u32 s29, s7, 0x20006
	s_cmp_eq_u32 s89, 16
	s_cselect_b64 s[20:21], -1, 0
	s_cmp_lg_u32 s89, 16
	s_cselect_b64 s[24:25], -1, 0
	s_or_b64 s[22:23], s[22:23], s[24:25]
	s_cmp_gt_i32 s10, 63
	s_cselect_b64 s[24:25], -1, 0
	v_readlane_b32 s78, v254, 8
	s_or_b64 s[22:23], s[22:23], s[24:25]
	v_readlane_b32 s76, v254, 6
	v_readlane_b32 s79, v254, 9
	v_readlane_b32 s80, v254, 21
	v_and_b32_e32 v182, 15, v12
	v_bfe_u32 v183, v12, 4, 2
	s_andn2_b64 vcc, exec, s[22:23]
	s_mov_b64 s[22:23], -1
	v_readlane_b32 s77, v254, 7
	v_readlane_b32 s75, v254, 10
	v_readlane_b32 s81, v254, 22
	s_movk_i32 s79, 0x5000
	s_mov_b32 s82, 0x1400000
	s_mov_b32 s83, 0x1800000
	s_mov_b32 s84, 0x1c00000
	s_mov_b32 s85, 0xf800000
	s_movk_i32 s86, 0x1000
	s_movk_i32 s87, 0x48
	s_movk_i32 s88, 0x1600
	s_cbranch_vccz .LBB0_970
	s_waitcnt vmcnt(0)
	v_lshl_or_b32 v14, s28, 6, v182
	s_lshl_b32 s100, s8, 8
	s_lshl_b32 s101, s29, 5
	s_or_b32 s100, s100, s101
	v_lshl_or_b32 v225, v183, 2, s100
	v_lshlrev_b32_e32 v222, 2, v225
	s_lshl_b32 s100, s10, 8
	v_add_u32_e32 v12, s100, v14
	v_lshl_add_u32 v12, v12, 10, v225
	v_lshlrev_b32_e32 v220, 2, v12
	v_mov_b32_e32 v224, v220
	v_lshlrev_b32_e32 v221, 2, v14
	s_lshl_b32 s100, s29, 4
	v_lshl_add_u32 v223, v14, 6, s100
	v_lshl_add_u32 v223, v183, 2, v223
	s_lshr_b32 s100, s10, 3
	s_mul_i32 s100, s100, 0x9000
	s_add_u32 s100, s47, s100
	s_addc_u32 s101, s62, 0
	global_load_dwordx4 v[140:143], v222, s[100:101]
	global_load_dwordx4 v[144:147], v222, s[100:101] offset:64
	global_load_dwordx4 v[148:151], v222, s[100:101] offset:512
	global_load_dwordx4 v[152:155], v222, s[100:101] offset:576
	global_load_dwordx4 v[156:159], v224, s[2:3]
	global_load_dwordx4 v[160:163], v224, s[2:3] offset:64
	global_load_dwordx4 v[164:167], v224, s[2:3] offset:512
	global_load_dwordx4 v[168:171], v224, s[2:3] offset:576
	v_add_u32_e32 v224, 0x10000, v224
	global_load_dwordx4 v[172:175], v224, s[2:3]
	global_load_dwordx4 v[176:179], v224, s[2:3] offset:64
	global_load_dwordx4 v[180:183], v224, s[2:3] offset:512
	global_load_dwordx4 v[184:187], v224, s[2:3] offset:576
	v_add_u32_e32 v224, 0x10000, v224
	global_load_dwordx4 v[188:191], v224, s[2:3]
	global_load_dwordx4 v[192:195], v224, s[2:3] offset:64
	global_load_dwordx4 v[196:199], v224, s[2:3] offset:512
	global_load_dwordx4 v[200:203], v224, s[2:3] offset:576
	v_add_u32_e32 v224, 0x10000, v224
	global_load_dwordx4 v[204:207], v224, s[2:3]
	global_load_dwordx4 v[208:211], v224, s[2:3] offset:64
	global_load_dwordx4 v[212:215], v224, s[2:3] offset:512
	global_load_dwordx4 v[228:231], v224, s[2:3] offset:576
	v_add_u32_e32 v224, 0x50000, v224
	s_waitcnt vmcnt(12)
	v_pk_fma_f32 v[128:129], v[128:129], v[140:141], v[156:157]
	v_pk_fma_f32 v[130:131], v[130:131], v[142:143], v[158:159]
	v_pk_fma_f32 v[124:125], v[124:125], v[144:145], v[160:161]
	v_pk_fma_f32 v[126:127], v[126:127], v[146:147], v[162:163]
	v_pk_fma_f32 v[120:121], v[120:121], v[148:149], v[164:165]
	v_pk_fma_f32 v[122:123], v[122:123], v[150:151], v[166:167]
	v_pk_fma_f32 v[116:117], v[116:117], v[152:153], v[168:169]
	v_pk_fma_f32 v[118:119], v[118:119], v[154:155], v[170:171]
	global_load_dwordx4 v[156:159], v224, s[2:3]
	global_load_dwordx4 v[160:163], v224, s[2:3] offset:64
	global_load_dwordx4 v[164:167], v224, s[2:3] offset:512
	global_load_dwordx4 v[168:171], v224, s[2:3] offset:576
	v_add_u32_e32 v224, 0x10000, v224
	v_mul_f32_e32 v132, v129, v129
	v_mul_f32_e32 v133, v131, v131
	v_fmac_f32_e32 v132, v128, v128
	v_fmac_f32_e32 v133, v130, v130
	v_add_f32_e32 v134, v132, v133
	v_mul_f32_e32 v132, v125, v125
	v_mul_f32_e32 v133, v127, v127
	v_fmac_f32_e32 v132, v124, v124
	v_fmac_f32_e32 v133, v126, v126
	v_add_f32_e32 v132, v132, v133
	v_add_f32_e32 v134, v134, v132
	v_mul_f32_e32 v132, v121, v121
	v_mul_f32_e32 v133, v123, v123
	v_fmac_f32_e32 v132, v120, v120
	v_fmac_f32_e32 v133, v122, v122
	v_add_f32_e32 v132, v132, v133
	v_add_f32_e32 v134, v134, v132
	v_mul_f32_e32 v132, v117, v117
	v_mul_f32_e32 v133, v119, v119
	v_fmac_f32_e32 v132, v116, v116
	v_fmac_f32_e32 v133, v118, v118
	v_add_f32_e32 v132, v132, v133
	v_add_f32_e32 v134, v134, v132
	ds_write_b32 v223, v134
	s_waitcnt vmcnt(12)
	v_pk_fma_f32 v[112:113], v[112:113], v[140:141], v[172:173]
	v_pk_fma_f32 v[114:115], v[114:115], v[142:143], v[174:175]
	v_pk_fma_f32 v[108:109], v[108:109], v[144:145], v[176:177]
	v_pk_fma_f32 v[110:111], v[110:111], v[146:147], v[178:179]
	v_pk_fma_f32 v[104:105], v[104:105], v[148:149], v[180:181]
	v_pk_fma_f32 v[106:107], v[106:107], v[150:151], v[182:183]
	v_pk_fma_f32 v[100:101], v[100:101], v[152:153], v[184:185]
	v_pk_fma_f32 v[102:103], v[102:103], v[154:155], v[186:187]
	global_load_dwordx4 v[172:175], v224, s[2:3]
	global_load_dwordx4 v[176:179], v224, s[2:3] offset:64
	global_load_dwordx4 v[180:183], v224, s[2:3] offset:512
	global_load_dwordx4 v[184:187], v224, s[2:3] offset:576
	v_add_u32_e32 v224, 0x10000, v224
	v_mul_f32_e32 v132, v113, v113
	v_mul_f32_e32 v133, v115, v115
	v_fmac_f32_e32 v132, v112, v112
	v_fmac_f32_e32 v133, v114, v114
	v_add_f32_e32 v135, v132, v133
	v_mul_f32_e32 v132, v109, v109
	v_mul_f32_e32 v133, v111, v111
	v_fmac_f32_e32 v132, v108, v108
	v_fmac_f32_e32 v133, v110, v110
	v_add_f32_e32 v132, v132, v133
	v_add_f32_e32 v135, v135, v132
	v_mul_f32_e32 v132, v105, v105
	v_mul_f32_e32 v133, v107, v107
	v_fmac_f32_e32 v132, v104, v104
	v_fmac_f32_e32 v133, v106, v106
	v_add_f32_e32 v132, v132, v133
	v_add_f32_e32 v135, v135, v132
	v_mul_f32_e32 v132, v101, v101
	v_mul_f32_e32 v133, v103, v103
	v_fmac_f32_e32 v132, v100, v100
	v_fmac_f32_e32 v133, v102, v102
	v_add_f32_e32 v132, v132, v133
	v_add_f32_e32 v135, v135, v132
	ds_write_b32 v223, v135 offset:1024
	s_waitcnt vmcnt(12)
	v_pk_fma_f32 v[96:97], v[96:97], v[140:141], v[188:189]
	v_pk_fma_f32 v[98:99], v[98:99], v[142:143], v[190:191]
	v_pk_fma_f32 v[92:93], v[92:93], v[144:145], v[192:193]
	v_pk_fma_f32 v[94:95], v[94:95], v[146:147], v[194:195]
	v_pk_fma_f32 v[88:89], v[88:89], v[148:149], v[196:197]
	v_pk_fma_f32 v[90:91], v[90:91], v[150:151], v[198:199]
	v_pk_fma_f32 v[84:85], v[84:85], v[152:153], v[200:201]
	v_pk_fma_f32 v[86:87], v[86:87], v[154:155], v[202:203]
	global_load_dwordx4 v[188:191], v224, s[2:3]
	global_load_dwordx4 v[192:195], v224, s[2:3] offset:64
	global_load_dwordx4 v[196:199], v224, s[2:3] offset:512
	global_load_dwordx4 v[200:203], v224, s[2:3] offset:576
	v_add_u32_e32 v224, 0x10000, v224
	v_mul_f32_e32 v132, v97, v97
	v_mul_f32_e32 v133, v99, v99
	v_fmac_f32_e32 v132, v96, v96
	v_fmac_f32_e32 v133, v98, v98
	v_add_f32_e32 v134, v132, v133
	v_mul_f32_e32 v132, v93, v93
	v_mul_f32_e32 v133, v95, v95
	v_fmac_f32_e32 v132, v92, v92
	v_fmac_f32_e32 v133, v94, v94
	v_add_f32_e32 v132, v132, v133
	v_add_f32_e32 v134, v134, v132
	v_mul_f32_e32 v132, v89, v89
	v_mul_f32_e32 v133, v91, v91
	v_fmac_f32_e32 v132, v88, v88
	v_fmac_f32_e32 v133, v90, v90
	v_add_f32_e32 v132, v132, v133
	v_add_f32_e32 v134, v134, v132
	v_mul_f32_e32 v132, v85, v85
	v_mul_f32_e32 v133, v87, v87
	v_fmac_f32_e32 v132, v84, v84
	v_fmac_f32_e32 v133, v86, v86
	v_add_f32_e32 v132, v132, v133
	v_add_f32_e32 v134, v134, v132
	ds_write_b32 v223, v134 offset:2048
	s_waitcnt vmcnt(12)
	v_pk_fma_f32 v[80:81], v[80:81], v[140:141], v[204:205]
	v_pk_fma_f32 v[82:83], v[82:83], v[142:143], v[206:207]
	v_pk_fma_f32 v[76:77], v[76:77], v[144:145], v[208:209]
	v_pk_fma_f32 v[78:79], v[78:79], v[146:147], v[210:211]
	v_pk_fma_f32 v[72:73], v[72:73], v[148:149], v[212:213]
	v_pk_fma_f32 v[74:75], v[74:75], v[150:151], v[214:215]
	v_pk_fma_f32 v[68:69], v[68:69], v[152:153], v[228:229]
	v_pk_fma_f32 v[70:71], v[70:71], v[154:155], v[230:231]
	global_load_dwordx4 v[204:207], v224, s[2:3]
	global_load_dwordx4 v[208:211], v224, s[2:3] offset:64
	global_load_dwordx4 v[212:215], v224, s[2:3] offset:512
	global_load_dwordx4 v[228:231], v224, s[2:3] offset:576
	v_mul_f32_e32 v132, v81, v81
	v_mul_f32_e32 v133, v83, v83
	v_fmac_f32_e32 v132, v80, v80
	v_fmac_f32_e32 v133, v82, v82
	v_add_f32_e32 v135, v132, v133
	v_mul_f32_e32 v132, v77, v77
	v_mul_f32_e32 v133, v79, v79
	v_fmac_f32_e32 v132, v76, v76
	v_fmac_f32_e32 v133, v78, v78
	v_add_f32_e32 v132, v132, v133
	v_add_f32_e32 v135, v135, v132
	v_mul_f32_e32 v132, v73, v73
	v_mul_f32_e32 v133, v75, v75
	v_fmac_f32_e32 v132, v72, v72
	v_fmac_f32_e32 v133, v74, v74
	v_add_f32_e32 v132, v132, v133
	v_add_f32_e32 v135, v135, v132
	v_mul_f32_e32 v132, v69, v69
	v_mul_f32_e32 v133, v71, v71
	v_fmac_f32_e32 v132, v68, v68
	v_fmac_f32_e32 v133, v70, v70
	v_add_f32_e32 v132, v132, v133
	v_add_f32_e32 v135, v135, v132
	ds_write_b32 v223, v135 offset:3072
	s_waitcnt vmcnt(12)
	v_pk_fma_f32 v[64:65], v[64:65], v[140:141], v[156:157]
	v_pk_fma_f32 v[66:67], v[66:67], v[142:143], v[158:159]
	v_pk_fma_f32 v[60:61], v[60:61], v[144:145], v[160:161]
	v_pk_fma_f32 v[62:63], v[62:63], v[146:147], v[162:163]
	v_pk_fma_f32 v[56:57], v[56:57], v[148:149], v[164:165]
	v_pk_fma_f32 v[58:59], v[58:59], v[150:151], v[166:167]
	v_pk_fma_f32 v[52:53], v[52:53], v[152:153], v[168:169]
	v_pk_fma_f32 v[54:55], v[54:55], v[154:155], v[170:171]
	v_mul_f32_e32 v132, v65, v65
	v_mul_f32_e32 v133, v67, v67
	v_fmac_f32_e32 v132, v64, v64
	v_fmac_f32_e32 v133, v66, v66
	v_add_f32_e32 v134, v132, v133
	v_mul_f32_e32 v132, v61, v61
	v_mul_f32_e32 v133, v63, v63
	v_fmac_f32_e32 v132, v60, v60
	v_fmac_f32_e32 v133, v62, v62
	v_add_f32_e32 v132, v132, v133
	v_add_f32_e32 v134, v134, v132
	v_mul_f32_e32 v132, v57, v57
	v_mul_f32_e32 v133, v59, v59
	v_fmac_f32_e32 v132, v56, v56
	v_fmac_f32_e32 v133, v58, v58
	v_add_f32_e32 v132, v132, v133
	v_add_f32_e32 v134, v134, v132
	v_mul_f32_e32 v132, v53, v53
	v_mul_f32_e32 v133, v55, v55
	v_fmac_f32_e32 v132, v52, v52
	v_fmac_f32_e32 v133, v54, v54
	v_add_f32_e32 v132, v132, v133
	v_add_f32_e32 v134, v134, v132
	ds_write_b32 v223, v134 offset:8192
	s_waitcnt vmcnt(8)
	v_pk_fma_f32 v[48:49], v[48:49], v[140:141], v[172:173]
	v_pk_fma_f32 v[50:51], v[50:51], v[142:143], v[174:175]
	v_pk_fma_f32 v[44:45], v[44:45], v[144:145], v[176:177]
	v_pk_fma_f32 v[46:47], v[46:47], v[146:147], v[178:179]
	v_pk_fma_f32 v[40:41], v[40:41], v[148:149], v[180:181]
	v_pk_fma_f32 v[42:43], v[42:43], v[150:151], v[182:183]
	v_pk_fma_f32 v[36:37], v[36:37], v[152:153], v[184:185]
	v_pk_fma_f32 v[38:39], v[38:39], v[154:155], v[186:187]
	v_mul_f32_e32 v132, v49, v49
	v_mul_f32_e32 v133, v51, v51
	v_fmac_f32_e32 v132, v48, v48
	v_fmac_f32_e32 v133, v50, v50
	v_add_f32_e32 v135, v132, v133
	v_mul_f32_e32 v132, v45, v45
	v_mul_f32_e32 v133, v47, v47
	v_fmac_f32_e32 v132, v44, v44
	v_fmac_f32_e32 v133, v46, v46
	v_add_f32_e32 v132, v132, v133
	v_add_f32_e32 v135, v135, v132
	v_mul_f32_e32 v132, v41, v41
	v_mul_f32_e32 v133, v43, v43
	v_fmac_f32_e32 v132, v40, v40
	v_fmac_f32_e32 v133, v42, v42
	v_add_f32_e32 v132, v132, v133
	v_add_f32_e32 v135, v135, v132
	v_mul_f32_e32 v132, v37, v37
	v_mul_f32_e32 v133, v39, v39
	v_fmac_f32_e32 v132, v36, v36
	v_fmac_f32_e32 v133, v38, v38
	v_add_f32_e32 v132, v132, v133
	v_add_f32_e32 v135, v135, v132
	ds_write_b32 v223, v135 offset:9216
	s_waitcnt vmcnt(4)
	v_pk_fma_f32 v[32:33], v[32:33], v[140:141], v[188:189]
	v_pk_fma_f32 v[34:35], v[34:35], v[142:143], v[190:191]
	v_pk_fma_f32 v[28:29], v[28:29], v[144:145], v[192:193]
	v_pk_fma_f32 v[30:31], v[30:31], v[146:147], v[194:195]
	v_pk_fma_f32 v[24:25], v[24:25], v[148:149], v[196:197]
	v_pk_fma_f32 v[26:27], v[26:27], v[150:151], v[198:199]
	v_pk_fma_f32 v[20:21], v[20:21], v[152:153], v[200:201]
	v_pk_fma_f32 v[22:23], v[22:23], v[154:155], v[202:203]
	v_mul_f32_e32 v132, v33, v33
	v_mul_f32_e32 v133, v35, v35
	v_fmac_f32_e32 v132, v32, v32
	v_fmac_f32_e32 v133, v34, v34
	v_add_f32_e32 v134, v132, v133
	v_mul_f32_e32 v132, v29, v29
	v_mul_f32_e32 v133, v31, v31
	v_fmac_f32_e32 v132, v28, v28
	v_fmac_f32_e32 v133, v30, v30
	v_add_f32_e32 v132, v132, v133
	v_add_f32_e32 v134, v134, v132
	v_mul_f32_e32 v132, v25, v25
	v_mul_f32_e32 v133, v27, v27
	v_fmac_f32_e32 v132, v24, v24
	v_fmac_f32_e32 v133, v26, v26
	v_add_f32_e32 v132, v132, v133
	v_add_f32_e32 v134, v134, v132
	v_mul_f32_e32 v132, v21, v21
	v_mul_f32_e32 v133, v23, v23
	v_fmac_f32_e32 v132, v20, v20
	v_fmac_f32_e32 v133, v22, v22
	v_add_f32_e32 v132, v132, v133
	v_add_f32_e32 v134, v134, v132
	ds_write_b32 v223, v134 offset:10240
	s_waitcnt vmcnt(0)
	v_pk_fma_f32 v[16:17], v[16:17], v[140:141], v[204:205]
	v_pk_fma_f32 v[18:19], v[18:19], v[142:143], v[206:207]
	v_pk_fma_f32 v[8:9], v[8:9], v[144:145], v[208:209]
	v_pk_fma_f32 v[10:11], v[10:11], v[146:147], v[210:211]
	v_pk_fma_f32 v[4:5], v[4:5], v[148:149], v[212:213]
	v_pk_fma_f32 v[6:7], v[6:7], v[150:151], v[214:215]
	v_pk_fma_f32 v[0:1], v[0:1], v[152:153], v[228:229]
	v_pk_fma_f32 v[2:3], v[2:3], v[154:155], v[230:231]
	v_mul_f32_e32 v132, v17, v17
	v_mul_f32_e32 v133, v19, v19
	v_fmac_f32_e32 v132, v16, v16
	v_fmac_f32_e32 v133, v18, v18
	v_add_f32_e32 v135, v132, v133
	v_mul_f32_e32 v132, v9, v9
	v_mul_f32_e32 v133, v11, v11
	v_fmac_f32_e32 v132, v8, v8
	v_fmac_f32_e32 v133, v10, v10
	v_add_f32_e32 v132, v132, v133
	v_add_f32_e32 v135, v135, v132
	v_mul_f32_e32 v132, v5, v5
	v_mul_f32_e32 v133, v7, v7
	v_fmac_f32_e32 v132, v4, v4
	v_fmac_f32_e32 v133, v6, v6
	v_add_f32_e32 v132, v132, v133
	v_add_f32_e32 v135, v135, v132
	v_mul_f32_e32 v132, v1, v1
	v_mul_f32_e32 v133, v3, v3
	v_fmac_f32_e32 v132, v0, v0
	v_fmac_f32_e32 v133, v2, v2
	v_add_f32_e32 v132, v132, v133
	v_add_f32_e32 v135, v135, v132
	ds_write_b32 v223, v135 offset:11264
	v_and_b32_e32 v15, 63, v216
	s_add_u32 s24, s0, 0x11200000
	s_addc_u32 s25, s1, 0
	s_waitcnt lgkmcnt(0)
	s_barrier
	s_and_b32 s0, s7, 0xffffffc0
	v_or_b32_e32 v12, s0, v15
	s_movk_i32 s0, 0x100
	v_cmp_gt_i32_e64 s[0:1], s0, v12
	s_waitcnt lgkmcnt(0)
	v_lshl_add_u32 v132, s10, 8, v12
	s_and_saveexec_b64 s[26:27], s[0:1]
	s_cbranch_execz .LBB0_954
	v_lshl_add_u32 v133, v12, 6, 0
	ds_read_b128 v[140:143], v133
	ds_read_b128 v[144:147], v133 offset:16
	ds_read_b128 v[148:151], v133 offset:32
	ds_read_b128 v[152:155], v133 offset:48
	v_ashrrev_i32_e32 v133, 31, v132
	s_ashr_i32 s9, s8, 31
	s_waitcnt lgkmcnt(0)
	v_add_f32_e32 v140, v140, v141
	v_add_f32_e32 v142, v142, v143
	v_add_f32_e32 v134, v140, v142
	v_add_f32_e32 v144, v144, v145
	v_add_f32_e32 v146, v146, v147
	v_add_f32_e32 v135, v144, v146
	v_add_f32_e32 v148, v148, v149
	v_add_f32_e32 v150, v150, v151
	v_add_f32_e32 v136, v148, v150
	v_add_f32_e32 v152, v152, v153
	v_add_f32_e32 v154, v154, v155
	v_add_f32_e32 v137, v152, v154
	v_mov_b32_e32 v138, v135
	v_mov_b32_e32 v139, v136
	v_mov_b32_e32 v135, v137
	v_pk_add_f32 v[134:135], v[138:139], v[134:135]
	v_lshl_add_u64 v[136:137], v[132:133], 4, s[24:25]
	v_pk_add_f32 v[134:135], v[134:135], v[134:135] op_sel:[0,1] op_sel_hi:[1,0]
	v_lshl_add_u64 v[136:137], s[8:9], 2, v[136:137]
	global_store_dword v[136:137], v134, off sc1

.LBB0_957:
	s_or_b64 exec, exec, s[16:17]
	v_mov_b32_e32 v224, v220
	global_store_dwordx4 v224, v[128:131], s[4:5]
	global_store_dwordx4 v224, v[124:127], s[4:5] offset:64
	global_store_dwordx4 v224, v[120:123], s[4:5] offset:512
	global_store_dwordx4 v224, v[116:119], s[4:5] offset:576
	v_add_u32_e32 v224, 0x10000, v224
	global_store_dwordx4 v224, v[112:115], s[4:5]
	global_store_dwordx4 v224, v[108:111], s[4:5] offset:64
	global_store_dwordx4 v224, v[104:107], s[4:5] offset:512
	global_store_dwordx4 v224, v[100:103], s[4:5] offset:576
	v_add_u32_e32 v224, 0x10000, v224
	global_store_dwordx4 v224, v[96:99], s[4:5]
	global_store_dwordx4 v224, v[92:95], s[4:5] offset:64
	global_store_dwordx4 v224, v[88:91], s[4:5] offset:512
	global_store_dwordx4 v224, v[84:87], s[4:5] offset:576
	v_add_u32_e32 v224, 0x10000, v224
	global_store_dwordx4 v224, v[80:83], s[4:5]
	global_store_dwordx4 v224, v[76:79], s[4:5] offset:64
	global_store_dwordx4 v224, v[72:75], s[4:5] offset:512
	global_store_dwordx4 v224, v[68:71], s[4:5] offset:576
	v_add_u32_e32 v224, 0x50000, v224
	global_store_dwordx4 v224, v[64:67], s[4:5]
	global_store_dwordx4 v224, v[60:63], s[4:5] offset:64
	global_store_dwordx4 v224, v[56:59], s[4:5] offset:512
	global_store_dwordx4 v224, v[52:55], s[4:5] offset:576
	v_add_u32_e32 v224, 0x10000, v224
	global_store_dwordx4 v224, v[48:51], s[4:5]
	global_store_dwordx4 v224, v[44:47], s[4:5] offset:64
	global_store_dwordx4 v224, v[40:43], s[4:5] offset:512
	global_store_dwordx4 v224, v[36:39], s[4:5] offset:576
	v_add_u32_e32 v224, 0x10000, v224
	global_store_dwordx4 v224, v[32:35], s[4:5]
	global_store_dwordx4 v224, v[28:31], s[4:5] offset:64
	global_store_dwordx4 v224, v[24:27], s[4:5] offset:512
	global_store_dwordx4 v224, v[20:23], s[4:5] offset:576
	v_add_u32_e32 v224, 0x10000, v224
	global_store_dwordx4 v224, v[16:19], s[4:5]
	global_store_dwordx4 v224, v[8:11], s[4:5] offset:64
	global_store_dwordx4 v224, v[4:7], s[4:5] offset:512
	global_store_dwordx4 v224, v[0:3], s[4:5] offset:576
	s_lshr_b32 s100, s10, 3
	s_mul_i32 s100, s100, 0x9000
	v_add_u32_e32 v225, 0x1000, v222
	s_add_u32 s100, s100, 0x46000
	s_add_u32 s100, s14, s100
	s_addc_u32 s101, s15, 0
	s_add_u32 s100, s18, s100
	s_addc_u32 s101, s19, s101
	global_load_dwordx4 v[156:159], v222, s[100:101]
	global_load_dwordx4 v[160:163], v222, s[100:101] offset:64
	global_load_dwordx4 v[164:167], v222, s[100:101] offset:512
	global_load_dwordx4 v[168:171], v222, s[100:101] offset:576
	global_load_dwordx4 v[172:175], v225, s[100:101]
	global_load_dwordx4 v[176:179], v225, s[100:101] offset:64
	global_load_dwordx4 v[180:183], v225, s[100:101] offset:512
	global_load_dwordx4 v[184:187], v225, s[100:101] offset:576
	s_cmp_gt_u32 s7, 63
	s_cbranch_scc1 .LBB0_967
	s_lshl_b32 s16, s10, 4
	s_ashr_i32 s17, s16, 31
	s_lshl_b64 s[16:17], s[16:17], 2
	s_add_u32 s16, s9, s16
	s_addc_u32 s17, s11, s17
	s_mov_b32 s7, 0x400001
	s_branch .LBB0_960

.LBB0_967:
	s_waitcnt vmcnt(0) lgkmcnt(0)
	s_barrier
	s_and_saveexec_b64 s[16:17], s[0:1]
	s_cbranch_execz .LBB0_969
	v_ashrrev_i32_e32 v133, 31, v132
	v_lshl_add_u64 v[132:133], v[132:133], 4, s[24:25]
	global_load_dword v15, v[132:133], off sc1
	global_load_dword v134, v[132:133], off offset:4 sc1
	global_load_dword v135, v[132:133], off offset:8 sc1
	s_nop 0
	global_load_dword v132, v[132:133], off offset:12 sc1
	v_lshl_add_u32 v12, v12, 2, 0
	s_waitcnt vmcnt(3)
	v_add_f32_e32 v15, 0, v15
	s_waitcnt vmcnt(2)
	v_add_f32_e32 v15, v15, v134
	s_waitcnt vmcnt(1)
	v_add_f32_e32 v15, v15, v135
	s_waitcnt vmcnt(0)
	v_add_f32_e32 v15, v15, v132
	v_fmamk_f32 v15, v15, 0x3a800000, v218
	v_mul_f32_e32 v132, 0x4f800000, v15
	v_cmp_gt_f32_e32 vcc, s85, v15
	s_nop 1
	v_cndmask_b32_e32 v15, v15, v132, vcc
	v_sqrt_f32_e32 v132, v15
	s_nop 0
	v_add_u32_e32 v133, -1, v132
	v_add_u32_e32 v134, 1, v132
	v_fma_f32 v135, -v133, v132, v15
	v_fma_f32 v136, -v134, v132, v15
	v_cmp_ge_f32_e64 s[0:1], 0, v135
	s_nop 1
	v_cndmask_b32_e64 v132, v132, v133, s[0:1]
	v_cmp_lt_f32_e64 s[0:1], 0, v136
	s_nop 1
	v_cndmask_b32_e64 v132, v132, v134, s[0:1]
	v_mul_f32_e32 v133, 0x37800000, v132
	v_cndmask_b32_e32 v132, v132, v133, vcc
	v_cmp_class_f32_e32 vcc, v15, v219
	s_nop 1
	v_cndmask_b32_e32 v15, v132, v15, vcc
	v_div_scale_f32 v132, s[0:1], v15, v15, 1.0
	v_rcp_f32_e32 v133, v132
	v_div_scale_f32 v134, vcc, 1.0, v15, 1.0
	v_fma_f32 v135, -v132, v133, 1.0
	v_fmac_f32_e32 v133, v135, v133
	v_mul_f32_e32 v135, v134, v133
	v_fma_f32 v136, -v132, v135, v134
	v_fmac_f32_e32 v135, v136, v133
	v_fma_f32 v132, -v132, v135, v134
	v_div_fmas_f32 v132, v132, v133, v135
	v_div_fixup_f32 v15, v132, v15, 1.0
	ds_write_b32 v12, v15 offset:16384
.LBB0_969:
	s_or_b64 exec, exec, s[16:17]
	s_waitcnt vmcnt(0) lgkmcnt(0)
	s_barrier
	ds_read_b32 v188, v221 offset:16384
	ds_read_b32 v190, v221 offset:16448
	ds_read_b32 v192, v221 offset:16512
	ds_read_b32 v194, v221 offset:16576
	ds_read_b32 v196, v221 offset:16896
	ds_read_b32 v198, v221 offset:16960
	ds_read_b32 v200, v221 offset:17024
	ds_read_b32 v202, v221 offset:17088
	s_add_u32 s100, s12, 0x3100000
	s_addc_u32 s101, s13, 0
	v_lshrrev_b32_e32 v224, 1, v220
	v_pk_add_f32 v[172:173], v[172:173], 1.0 op_sel_hi:[1,0]
	v_pk_add_f32 v[174:175], v[174:175], 1.0 op_sel_hi:[1,0]
	v_pk_add_f32 v[176:177], v[176:177], 1.0 op_sel_hi:[1,0]
	v_pk_add_f32 v[178:179], v[178:179], 1.0 op_sel_hi:[1,0]
	v_pk_add_f32 v[180:181], v[180:181], 1.0 op_sel_hi:[1,0]
	v_pk_add_f32 v[182:183], v[182:183], 1.0 op_sel_hi:[1,0]
	v_pk_add_f32 v[184:185], v[184:185], 1.0 op_sel_hi:[1,0]
	v_pk_add_f32 v[186:187], v[186:187], 1.0 op_sel_hi:[1,0]
	s_waitcnt lgkmcnt(0)
	v_pk_mul_f32 v[132:133], v[128:129], v[188:189] op_sel_hi:[1,0]
	v_pk_mul_f32 v[134:135], v[130:131], v[188:189] op_sel_hi:[1,0]
	v_pk_fma_f32 v[132:133], v[172:173], v[132:133], v[156:157]
	v_pk_fma_f32 v[134:135], v[174:175], v[134:135], v[158:159]
	v_cvt_pk_bf16_f32 v132, v132, v133
	v_cvt_pk_bf16_f32 v133, v134, v135
	global_store_dwordx2 v224, v[132:133], s[100:101]
	v_pk_mul_f32 v[136:137], v[124:125], v[188:189] op_sel_hi:[1,0]
	v_pk_mul_f32 v[138:139], v[126:127], v[188:189] op_sel_hi:[1,0]
	v_pk_fma_f32 v[136:137], v[176:177], v[136:137], v[160:161]
	v_pk_fma_f32 v[138:139], v[178:179], v[138:139], v[162:163]
	v_cvt_pk_bf16_f32 v136, v136, v137
	v_cvt_pk_bf16_f32 v137, v138, v139
	global_store_dwordx2 v224, v[136:137], s[100:101] offset:32
	v_pk_mul_f32 v[140:141], v[120:121], v[188:189] op_sel_hi:[1,0]
	v_pk_mul_f32 v[142:143], v[122:123], v[188:189] op_sel_hi:[1,0]
	v_pk_fma_f32 v[140:141], v[180:181], v[140:141], v[164:165]
	v_pk_fma_f32 v[142:143], v[182:183], v[142:143], v[166:167]
	v_cvt_pk_bf16_f32 v140, v140, v141
	v_cvt_pk_bf16_f32 v141, v142, v143
	global_store_dwordx2 v224, v[140:141], s[100:101] offset:256
	v_pk_mul_f32 v[144:145], v[116:117], v[188:189] op_sel_hi:[1,0]
	v_pk_mul_f32 v[146:147], v[118:119], v[188:189] op_sel_hi:[1,0]
	v_pk_fma_f32 v[144:145], v[184:185], v[144:145], v[168:169]
	v_pk_fma_f32 v[146:147], v[186:187], v[146:147], v[170:171]
	v_cvt_pk_bf16_f32 v144, v144, v145
	v_cvt_pk_bf16_f32 v145, v146, v147
	global_store_dwordx2 v224, v[144:145], s[100:101] offset:288
	v_add_u32_e32 v224, 0x8000, v224
	v_pk_mul_f32 v[132:133], v[112:113], v[190:191] op_sel_hi:[1,0]
	v_pk_mul_f32 v[134:135], v[114:115], v[190:191] op_sel_hi:[1,0]
	v_pk_fma_f32 v[132:133], v[172:173], v[132:133], v[156:157]
	v_pk_fma_f32 v[134:135], v[174:175], v[134:135], v[158:159]
	v_cvt_pk_bf16_f32 v132, v132, v133
	v_cvt_pk_bf16_f32 v133, v134, v135
	global_store_dwordx2 v224, v[132:133], s[100:101]
	v_pk_mul_f32 v[136:137], v[108:109], v[190:191] op_sel_hi:[1,0]
	v_pk_mul_f32 v[138:139], v[110:111], v[190:191] op_sel_hi:[1,0]
	v_pk_fma_f32 v[136:137], v[176:177], v[136:137], v[160:161]
	v_pk_fma_f32 v[138:139], v[178:179], v[138:139], v[162:163]
	v_cvt_pk_bf16_f32 v136, v136, v137
	v_cvt_pk_bf16_f32 v137, v138, v139
	global_store_dwordx2 v224, v[136:137], s[100:101] offset:32
	v_pk_mul_f32 v[140:141], v[104:105], v[190:191] op_sel_hi:[1,0]
	v_pk_mul_f32 v[142:143], v[106:107], v[190:191] op_sel_hi:[1,0]
	v_pk_fma_f32 v[140:141], v[180:181], v[140:141], v[164:165]
	v_pk_fma_f32 v[142:143], v[182:183], v[142:143], v[166:167]
	v_cvt_pk_bf16_f32 v140, v140, v141
	v_cvt_pk_bf16_f32 v141, v142, v143
	global_store_dwordx2 v224, v[140:141], s[100:101] offset:256
	v_pk_mul_f32 v[144:145], v[100:101], v[190:191] op_sel_hi:[1,0]
	v_pk_mul_f32 v[146:147], v[102:103], v[190:191] op_sel_hi:[1,0]
	v_pk_fma_f32 v[144:145], v[184:185], v[144:145], v[168:169]
	v_pk_fma_f32 v[146:147], v[186:187], v[146:147], v[170:171]
	v_cvt_pk_bf16_f32 v144, v144, v145
	v_cvt_pk_bf16_f32 v145, v146, v147
	global_store_dwordx2 v224, v[144:145], s[100:101] offset:288
	v_add_u32_e32 v224, 0x8000, v224
	v_pk_mul_f32 v[132:133], v[96:97], v[192:193] op_sel_hi:[1,0]
	v_pk_mul_f32 v[134:135], v[98:99], v[192:193] op_sel_hi:[1,0]
	v_pk_fma_f32 v[132:133], v[172:173], v[132:133], v[156:157]
	v_pk_fma_f32 v[134:135], v[174:175], v[134:135], v[158:159]
	v_cvt_pk_bf16_f32 v132, v132, v133
	v_cvt_pk_bf16_f32 v133, v134, v135
	global_store_dwordx2 v224, v[132:133], s[100:101]
	v_pk_mul_f32 v[136:137], v[92:93], v[192:193] op_sel_hi:[1,0]
	v_pk_mul_f32 v[138:139], v[94:95], v[192:193] op_sel_hi:[1,0]
	v_pk_fma_f32 v[136:137], v[176:177], v[136:137], v[160:161]
	v_pk_fma_f32 v[138:139], v[178:179], v[138:139], v[162:163]
	v_cvt_pk_bf16_f32 v136, v136, v137
	v_cvt_pk_bf16_f32 v137, v138, v139
	global_store_dwordx2 v224, v[136:137], s[100:101] offset:32
	v_pk_mul_f32 v[140:141], v[88:89], v[192:193] op_sel_hi:[1,0]
	v_pk_mul_f32 v[142:143], v[90:91], v[192:193] op_sel_hi:[1,0]
	v_pk_fma_f32 v[140:141], v[180:181], v[140:141], v[164:165]
	v_pk_fma_f32 v[142:143], v[182:183], v[142:143], v[166:167]
	v_cvt_pk_bf16_f32 v140, v140, v141
	v_cvt_pk_bf16_f32 v141, v142, v143
	global_store_dwordx2 v224, v[140:141], s[100:101] offset:256
	v_pk_mul_f32 v[144:145], v[84:85], v[192:193] op_sel_hi:[1,0]
	v_pk_mul_f32 v[146:147], v[86:87], v[192:193] op_sel_hi:[1,0]
	v_pk_fma_f32 v[144:145], v[184:185], v[144:145], v[168:169]
	v_pk_fma_f32 v[146:147], v[186:187], v[146:147], v[170:171]
	v_cvt_pk_bf16_f32 v144, v144, v145
	v_cvt_pk_bf16_f32 v145, v146, v147
	global_store_dwordx2 v224, v[144:145], s[100:101] offset:288
	v_add_u32_e32 v224, 0x8000, v224
	v_pk_mul_f32 v[132:133], v[80:81], v[194:195] op_sel_hi:[1,0]
	v_pk_mul_f32 v[134:135], v[82:83], v[194:195] op_sel_hi:[1,0]
	v_pk_fma_f32 v[132:133], v[172:173], v[132:133], v[156:157]
	v_pk_fma_f32 v[134:135], v[174:175], v[134:135], v[158:159]
	v_cvt_pk_bf16_f32 v132, v132, v133
	v_cvt_pk_bf16_f32 v133, v134, v135
	global_store_dwordx2 v224, v[132:133], s[100:101]
	v_pk_mul_f32 v[136:137], v[76:77], v[194:195] op_sel_hi:[1,0]
	v_pk_mul_f32 v[138:139], v[78:79], v[194:195] op_sel_hi:[1,0]
	v_pk_fma_f32 v[136:137], v[176:177], v[136:137], v[160:161]
	v_pk_fma_f32 v[138:139], v[178:179], v[138:139], v[162:163]
	v_cvt_pk_bf16_f32 v136, v136, v137
	v_cvt_pk_bf16_f32 v137, v138, v139
	global_store_dwordx2 v224, v[136:137], s[100:101] offset:32
	v_pk_mul_f32 v[140:141], v[72:73], v[194:195] op_sel_hi:[1,0]
	v_pk_mul_f32 v[142:143], v[74:75], v[194:195] op_sel_hi:[1,0]
	v_pk_fma_f32 v[140:141], v[180:181], v[140:141], v[164:165]
	v_pk_fma_f32 v[142:143], v[182:183], v[142:143], v[166:167]
	v_cvt_pk_bf16_f32 v140, v140, v141
	v_cvt_pk_bf16_f32 v141, v142, v143
	global_store_dwordx2 v224, v[140:141], s[100:101] offset:256
	v_pk_mul_f32 v[144:145], v[68:69], v[194:195] op_sel_hi:[1,0]
	v_pk_mul_f32 v[146:147], v[70:71], v[194:195] op_sel_hi:[1,0]
	v_pk_fma_f32 v[144:145], v[184:185], v[144:145], v[168:169]
	v_pk_fma_f32 v[146:147], v[186:187], v[146:147], v[170:171]
	v_cvt_pk_bf16_f32 v144, v144, v145
	v_cvt_pk_bf16_f32 v145, v146, v147
	global_store_dwordx2 v224, v[144:145], s[100:101] offset:288
	v_add_u32_e32 v224, 0x28000, v224
	v_pk_mul_f32 v[132:133], v[64:65], v[196:197] op_sel_hi:[1,0]
	v_pk_mul_f32 v[134:135], v[66:67], v[196:197] op_sel_hi:[1,0]
	v_pk_fma_f32 v[132:133], v[172:173], v[132:133], v[156:157]
	v_pk_fma_f32 v[134:135], v[174:175], v[134:135], v[158:159]
	v_cvt_pk_bf16_f32 v132, v132, v133
	v_cvt_pk_bf16_f32 v133, v134, v135
	global_store_dwordx2 v224, v[132:133], s[100:101]
	v_pk_mul_f32 v[136:137], v[60:61], v[196:197] op_sel_hi:[1,0]
	v_pk_mul_f32 v[138:139], v[62:63], v[196:197] op_sel_hi:[1,0]
	v_pk_fma_f32 v[136:137], v[176:177], v[136:137], v[160:161]
	v_pk_fma_f32 v[138:139], v[178:179], v[138:139], v[162:163]
	v_cvt_pk_bf16_f32 v136, v136, v137
	v_cvt_pk_bf16_f32 v137, v138, v139
	global_store_dwordx2 v224, v[136:137], s[100:101] offset:32
	v_pk_mul_f32 v[140:141], v[56:57], v[196:197] op_sel_hi:[1,0]
	v_pk_mul_f32 v[142:143], v[58:59], v[196:197] op_sel_hi:[1,0]
	v_pk_fma_f32 v[140:141], v[180:181], v[140:141], v[164:165]
	v_pk_fma_f32 v[142:143], v[182:183], v[142:143], v[166:167]
	v_cvt_pk_bf16_f32 v140, v140, v141
	v_cvt_pk_bf16_f32 v141, v142, v143
	global_store_dwordx2 v224, v[140:141], s[100:101] offset:256
	v_pk_mul_f32 v[144:145], v[52:53], v[196:197] op_sel_hi:[1,0]
	v_pk_mul_f32 v[146:147], v[54:55], v[196:197] op_sel_hi:[1,0]
	v_pk_fma_f32 v[144:145], v[184:185], v[144:145], v[168:169]
	v_pk_fma_f32 v[146:147], v[186:187], v[146:147], v[170:171]
	v_cvt_pk_bf16_f32 v144, v144, v145
	v_cvt_pk_bf16_f32 v145, v146, v147
	global_store_dwordx2 v224, v[144:145], s[100:101] offset:288
	v_add_u32_e32 v224, 0x8000, v224
	v_pk_mul_f32 v[132:133], v[48:49], v[198:199] op_sel_hi:[1,0]
	v_pk_mul_f32 v[134:135], v[50:51], v[198:199] op_sel_hi:[1,0]
	v_pk_fma_f32 v[132:133], v[172:173], v[132:133], v[156:157]
	v_pk_fma_f32 v[134:135], v[174:175], v[134:135], v[158:159]
	v_cvt_pk_bf16_f32 v132, v132, v133
	v_cvt_pk_bf16_f32 v133, v134, v135
	global_store_dwordx2 v224, v[132:133], s[100:101]
	v_pk_mul_f32 v[136:137], v[44:45], v[198:199] op_sel_hi:[1,0]
	v_pk_mul_f32 v[138:139], v[46:47], v[198:199] op_sel_hi:[1,0]
	v_pk_fma_f32 v[136:137], v[176:177], v[136:137], v[160:161]
	v_pk_fma_f32 v[138:139], v[178:179], v[138:139], v[162:163]
	v_cvt_pk_bf16_f32 v136, v136, v137
	v_cvt_pk_bf16_f32 v137, v138, v139
	global_store_dwordx2 v224, v[136:137], s[100:101] offset:32
	v_pk_mul_f32 v[140:141], v[40:41], v[198:199] op_sel_hi:[1,0]
	v_pk_mul_f32 v[142:143], v[42:43], v[198:199] op_sel_hi:[1,0]
	v_pk_fma_f32 v[140:141], v[180:181], v[140:141], v[164:165]
	v_pk_fma_f32 v[142:143], v[182:183], v[142:143], v[166:167]
	v_cvt_pk_bf16_f32 v140, v140, v141
	v_cvt_pk_bf16_f32 v141, v142, v143
	global_store_dwordx2 v224, v[140:141], s[100:101] offset:256
	v_pk_mul_f32 v[144:145], v[36:37], v[198:199] op_sel_hi:[1,0]
	v_pk_mul_f32 v[146:147], v[38:39], v[198:199] op_sel_hi:[1,0]
	v_pk_fma_f32 v[144:145], v[184:185], v[144:145], v[168:169]
	v_pk_fma_f32 v[146:147], v[186:187], v[146:147], v[170:171]
	v_cvt_pk_bf16_f32 v144, v144, v145
	v_cvt_pk_bf16_f32 v145, v146, v147
	global_store_dwordx2 v224, v[144:145], s[100:101] offset:288
	v_add_u32_e32 v224, 0x8000, v224
	v_pk_mul_f32 v[132:133], v[32:33], v[200:201] op_sel_hi:[1,0]
	v_pk_mul_f32 v[134:135], v[34:35], v[200:201] op_sel_hi:[1,0]
	v_pk_fma_f32 v[132:133], v[172:173], v[132:133], v[156:157]
	v_pk_fma_f32 v[134:135], v[174:175], v[134:135], v[158:159]
	v_cvt_pk_bf16_f32 v132, v132, v133
	v_cvt_pk_bf16_f32 v133, v134, v135
	global_store_dwordx2 v224, v[132:133], s[100:101]
	v_pk_mul_f32 v[136:137], v[28:29], v[200:201] op_sel_hi:[1,0]
	v_pk_mul_f32 v[138:139], v[30:31], v[200:201] op_sel_hi:[1,0]
	v_pk_fma_f32 v[136:137], v[176:177], v[136:137], v[160:161]
	v_pk_fma_f32 v[138:139], v[178:179], v[138:139], v[162:163]
	v_cvt_pk_bf16_f32 v136, v136, v137
	v_cvt_pk_bf16_f32 v137, v138, v139
	global_store_dwordx2 v224, v[136:137], s[100:101] offset:32
	v_pk_mul_f32 v[140:141], v[24:25], v[200:201] op_sel_hi:[1,0]
	v_pk_mul_f32 v[142:143], v[26:27], v[200:201] op_sel_hi:[1,0]
	v_pk_fma_f32 v[140:141], v[180:181], v[140:141], v[164:165]
	v_pk_fma_f32 v[142:143], v[182:183], v[142:143], v[166:167]
	v_cvt_pk_bf16_f32 v140, v140, v141
	v_cvt_pk_bf16_f32 v141, v142, v143
	global_store_dwordx2 v224, v[140:141], s[100:101] offset:256
	v_pk_mul_f32 v[144:145], v[20:21], v[200:201] op_sel_hi:[1,0]
	v_pk_mul_f32 v[146:147], v[22:23], v[200:201] op_sel_hi:[1,0]
	v_pk_fma_f32 v[144:145], v[184:185], v[144:145], v[168:169]
	v_pk_fma_f32 v[146:147], v[186:187], v[146:147], v[170:171]
	v_cvt_pk_bf16_f32 v144, v144, v145
	v_cvt_pk_bf16_f32 v145, v146, v147
	global_store_dwordx2 v224, v[144:145], s[100:101] offset:288
	v_add_u32_e32 v224, 0x8000, v224
	v_pk_mul_f32 v[132:133], v[16:17], v[202:203] op_sel_hi:[1,0]
	v_pk_mul_f32 v[134:135], v[18:19], v[202:203] op_sel_hi:[1,0]
	v_pk_fma_f32 v[132:133], v[172:173], v[132:133], v[156:157]
	v_pk_fma_f32 v[134:135], v[174:175], v[134:135], v[158:159]
	v_cvt_pk_bf16_f32 v132, v132, v133
	v_cvt_pk_bf16_f32 v133, v134, v135
	global_store_dwordx2 v224, v[132:133], s[100:101]
	v_pk_mul_f32 v[136:137], v[8:9], v[202:203] op_sel_hi:[1,0]
	v_pk_mul_f32 v[138:139], v[10:11], v[202:203] op_sel_hi:[1,0]
	v_pk_fma_f32 v[136:137], v[176:177], v[136:137], v[160:161]
	v_pk_fma_f32 v[138:139], v[178:179], v[138:139], v[162:163]
	v_cvt_pk_bf16_f32 v136, v136, v137
	v_cvt_pk_bf16_f32 v137, v138, v139
	global_store_dwordx2 v224, v[136:137], s[100:101] offset:32
	v_pk_mul_f32 v[140:141], v[4:5], v[202:203] op_sel_hi:[1,0]
	v_pk_mul_f32 v[142:143], v[6:7], v[202:203] op_sel_hi:[1,0]
	v_pk_fma_f32 v[140:141], v[180:181], v[140:141], v[164:165]
	v_pk_fma_f32 v[142:143], v[182:183], v[142:143], v[166:167]
	v_cvt_pk_bf16_f32 v140, v140, v141
	v_cvt_pk_bf16_f32 v141, v142, v143
	global_store_dwordx2 v224, v[140:141], s[100:101] offset:256
	v_pk_mul_f32 v[144:145], v[0:1], v[202:203] op_sel_hi:[1,0]
	v_pk_mul_f32 v[146:147], v[2:3], v[202:203] op_sel_hi:[1,0]
	v_pk_fma_f32 v[144:145], v[184:185], v[144:145], v[168:169]
	v_pk_fma_f32 v[146:147], v[186:187], v[146:147], v[170:171]
	v_cvt_pk_bf16_f32 v144, v144, v145
	v_cvt_pk_bf16_f32 v145, v146, v147
	global_store_dwordx2 v224, v[144:145], s[100:101] offset:288
	s_mov_b64 s[22:23], 0
	s_branch .LBB0_970

	.amdhsa_kernel _Z10fwd_kernel4Args
		.amdhsa_group_segment_fixed_size 0
		.amdhsa_private_segment_fixed_size 0
		.amdhsa_kernarg_size 464
		.amdhsa_user_sgpr_count 2
		.amdhsa_user_sgpr_dispatch_ptr 0
		.amdhsa_user_sgpr_queue_ptr 0
		.amdhsa_user_sgpr_kernarg_segment_ptr 1
		.amdhsa_user_sgpr_dispatch_id 0
		.amdhsa_user_sgpr_kernarg_preload_length 0
		.amdhsa_user_sgpr_kernarg_preload_offset 0
		.amdhsa_user_sgpr_private_segment_size 0
		.amdhsa_uses_dynamic_stack 0
		.amdhsa_enable_private_segment 0
		.amdhsa_system_sgpr_workgroup_id_x 1
		.amdhsa_system_sgpr_workgroup_id_y 0
		.amdhsa_system_sgpr_workgroup_id_z 0
		.amdhsa_system_sgpr_workgroup_info 0
		.amdhsa_system_vgpr_workitem_id 2
		.amdhsa_next_free_vgpr 256
		.amdhsa_next_free_sgpr 102
		.amdhsa_accum_offset 256
		.amdhsa_reserve_vcc 1
		.amdhsa_float_round_mode_32 0
		.amdhsa_float_round_mode_16_64 0
		.amdhsa_float_denorm_mode_32 3
		.amdhsa_float_denorm_mode_16_64 3
		.amdhsa_dx10_clamp 1
		.amdhsa_ieee_mode 1
		.amdhsa_fp16_overflow 0
		.amdhsa_tg_split 0
		.amdhsa_exception_fp_ieee_invalid_op 0
		.amdhsa_exception_fp_denorm_src 0
		.amdhsa_exception_fp_ieee_div_zero 0
		.amdhsa_exception_fp_ieee_overflow 0
		.amdhsa_exception_fp_ieee_underflow 0
		.amdhsa_exception_fp_ieee_inexact 0
		.amdhsa_exception_int_div_zero 0
	.end_amdhsa_kernel

amdhsa.kernels:
  - .agpr_count:     0
    .args:
      - .offset:         0
        .size:           208
        .value_kind:     by_value
      - .offset:         208
        .size:           4
        .value_kind:     hidden_block_count_x
      - .offset:         212
        .size:           4
        .value_kind:     hidden_block_count_y
      - .offset:         216
        .size:           4
        .value_kind:     hidden_block_count_z
      - .offset:         220
        .size:           2
        .value_kind:     hidden_group_size_x
      - .offset:         222
        .size:           2
        .value_kind:     hidden_group_size_y
      - .offset:         224
        .size:           2
        .value_kind:     hidden_group_size_z
      - .offset:         226
        .size:           2
        .value_kind:     hidden_remainder_x
      - .offset:         228
        .size:           2
        .value_kind:     hidden_remainder_y
      - .offset:         230
        .size:           2
        .value_kind:     hidden_remainder_z
      - .offset:         248
        .size:           8
        .value_kind:     hidden_global_offset_x
      - .offset:         256
        .size:           8
        .value_kind:     hidden_global_offset_y
      - .offset:         264
        .size:           8
        .value_kind:     hidden_global_offset_z
      - .offset:         272
        .size:           2
        .value_kind:     hidden_grid_dims
      - .offset:         296
        .size:           8
        .value_kind:     hidden_multigrid_sync_arg
      - .offset:         328
        .size:           4
        .value_kind:     hidden_dynamic_lds_size
    .group_segment_fixed_size: 0
    .kernarg_segment_align: 8
    .kernarg_segment_size: 464
    .language:       OpenCL C
    .language_version:
      - 2
      - 0
    .max_flat_workgroup_size: 512
    .name:           _Z10fwd_kernel4Args
    .private_segment_fixed_size: 0
    .sgpr_count:     108
    .sgpr_spill_count: 124
    .symbol:         _Z10fwd_kernel4Args.kd
    .uniform_work_group_size: 1
    .uses_dynamic_stack: false
    .vgpr_count:     256
    .vgpr_spill_count: 0
    .wavefront_size: 64
